# scan pass 3 walks its items in reverse so it re-reads first what pass 1 read last (last-level cache reuse)
# speedup vs baseline: 1.0040x; 1.0040x over previous
; __global__ void __launch_bounds__(NTHREADS, 2) mega(Args args) {
;     ...
;                 for (int it = gw; it < BATCH * 72 * 22; it += NGW) {
;                     const int cg = it % 22, r1 = it / 22, q = r1 % 72, b = r1 / 72;
;                     const int ch = cg * 128 + 2 * lane;
;                     const int rbase = q < 8 ? ML + b * CTX + 32 * q : b * SEQ + 32 * (q - 8);
;                     const size_t ro = (size_t)rbase * LW + ch;
;                     const size_t c0 = ((size_t)(0 * BATCH + b) * 72 + q) * LW + ch, c1 = ((size_t)(1 * BATCH + b) * 72 + q) * LW + ch;
;                     float hf0[32], hf1[32];
;                     { u32x2 lb[32]; const f32x2 hc = *(const f32x2*)(CARRY + c0);
; #pragma unroll
;                       for (int t = 0; t < 32; ++t) lb[t] = *(const u32x2*)(LB + ro + (size_t)t * LW);
.LBB9_1043:
	s_waitcnt vmcnt(0)
	v_mov_b32_e32 v2, v0
	v_mov_b32_e32 v3, v241
	ds_read_b64 v[4:5], v3 offset:192
	v_readfirstlane_b32 s0, v2
	s_ashr_i32 s0, s0, 6
	v_readlane_b32 s1, v254, 11
	s_add_i32 s14, s0, s1
	s_waitcnt lgkmcnt(0)
	v_readfirstlane_b32 s4, v5
	v_readfirstlane_b32 s5, v4
	v_readlane_b32 s0, v254, 4
	s_cmpk_gt_i32 s14, 0x18bf
	s_cbranch_scc1 .LBB9_1050
	s_add_u32 s0, s5, 0x2e200000
	s_addc_u32 s1, s4, 0
	s_add_u32 s15, s5, 0x3ea00000
	s_addc_u32 s18, s4, 0
	s_add_u32 s38, s5, 0x1fb00000
	s_addc_u32 s39, s4, 0
	s_add_u32 s40, s5, 0x3aa00000
	s_addc_u32 s41, s4, 0
	v_lshlrev_b32_e32 v2, 1, v2
	s_add_u32 s42, s5, 0x34500000
	v_and_b32_e32 v2, 0x7e, v2
	s_addc_u32 s43, s4, 0
	v_readlane_b32 s4, v255, 9
	s_sub_i32 s80, 0x18bf, s14
	v_lshl_or_b32 v72, s80, 7, v2
	s_lshl_b32 s19, s4, 7
	v_readlane_b32 s5, v255, 10
	s_branch .LBB9_1046
.LBB9_1045:
	s_mulk_i32 s5, 0xf500
	v_add_u32_e32 v2, s5, v72
	v_ashrrev_i32_e32 v3, 31, v2
	v_mad_i64_i32 v[12:13], s[10:11], s20, v244, v[2:3]
	s_mul_i32 s3, s21, 0x48
	v_lshlrev_b64 v[4:5], 2, v[12:13]
	s_add_i32 s11, s3, s4
	v_lshl_add_u64 v[74:75], s[0:1], 0, v[4:5]
	s_movk_i32 s9, 0x2000
	s_add_i32 s10, s11, 0x120
	s_mul_hi_i32 s3, s11, 0x2c00
	s_mulk_i32 s11, 0x2c00
	v_add_co_u32_e32 v10, vcc, s9, v74
	s_add_u32 s4, s15, s11
	s_nop 0
	v_addc_co_u32_e32 v11, vcc, 0, v75, vcc
	s_movk_i32 s25, 0x5000
	s_addc_u32 s5, s18, s3
	v_lshlrev_b64 v[6:7], 2, v[2:3]
	v_add_co_u32_e32 v14, vcc, s25, v74
	v_lshl_add_u64 v[8:9], s[4:5], 0, v[6:7]
	s_nop 0
	v_addc_co_u32_e32 v15, vcc, 0, v75, vcc
	s_mov_b32 s22, 0x8000
	global_load_dwordx2 v[76:77], v[8:9], off
	global_load_dwordx2 v[78:79], v[74:75], off
	global_load_dwordx2 v[70:71], v[10:11], off offset:3072
	global_load_dwordx2 v[68:69], v[14:15], off offset:2048
	v_add_co_u32_e32 v8, vcc, s22, v74
	s_mov_b32 s24, 0xb000
	s_nop 0
	v_addc_co_u32_e32 v9, vcc, 0, v75, vcc
	v_add_co_u32_e32 v10, vcc, s24, v74
	s_mov_b32 s30, 0xd000
	s_nop 0
	v_addc_co_u32_e32 v11, vcc, 0, v75, vcc
	v_add_co_u32_e32 v14, vcc, s30, v74
	s_mov_b32 s31, 0x13000
	s_nop 0
	v_addc_co_u32_e32 v15, vcc, 0, v75, vcc
	v_add_co_u32_e32 v16, vcc, s16, v74
	s_mov_b32 s21, 0x16000
	s_nop 0
	v_addc_co_u32_e32 v17, vcc, 0, v75, vcc
	global_load_dwordx2 v[66:67], v[8:9], off offset:1024
	global_load_dwordx2 v[64:65], v[10:11], off
	global_load_dwordx2 v[62:63], v[14:15], off offset:3072
	global_load_dwordx2 v[60:61], v[16:17], off offset:2048
	v_add_co_u32_e32 v8, vcc, s31, v74
	s_mov_b32 s33, 0x18000
	s_nop 0
	v_addc_co_u32_e32 v9, vcc, 0, v75, vcc
	v_add_co_u32_e32 v10, vcc, s21, v74
	s_mov_b32 s34, 0x1b000
	s_nop 0
	v_addc_co_u32_e32 v11, vcc, 0, v75, vcc
	v_add_co_u32_e32 v14, vcc, s33, v74
	s_mov_b32 s23, 0x1e000
	s_nop 0
	v_addc_co_u32_e32 v15, vcc, 0, v75, vcc
	v_add_co_u32_e32 v16, vcc, s34, v74
	s_mov_b32 s35, 0x21000
	s_nop 0
	v_addc_co_u32_e32 v17, vcc, 0, v75, vcc
	global_load_dwordx2 v[58:59], v[8:9], off offset:1024
	global_load_dwordx2 v[56:57], v[10:11], off
	global_load_dwordx2 v[54:55], v[14:15], off offset:3072
	global_load_dwordx2 v[52:53], v[16:17], off offset:2048
	v_add_co_u32_e32 v8, vcc, s23, v74
	s_mov_b32 s48, 0x23000
	s_nop 0
	v_addc_co_u32_e32 v9, vcc, 0, v75, vcc
	v_add_co_u32_e32 v10, vcc, s35, v74
	s_mov_b32 s52, 0x26000
	s_nop 0
	v_addc_co_u32_e32 v11, vcc, 0, v75, vcc
	v_add_co_u32_e32 v14, vcc, s48, v74
	s_mov_b32 s53, 0x29000
	s_nop 0
	v_addc_co_u32_e32 v15, vcc, 0, v75, vcc
	v_add_co_u32_e32 v16, vcc, s52, v74
	s_mov_b32 s54, 0x2c000
	s_nop 0
	v_addc_co_u32_e32 v17, vcc, 0, v75, vcc
	global_load_dwordx2 v[50:51], v[8:9], off offset:1024
	global_load_dwordx2 v[48:49], v[10:11], off
	global_load_dwordx2 v[46:47], v[14:15], off offset:3072
	global_load_dwordx2 v[44:45], v[16:17], off offset:2048
	v_add_co_u32_e32 v8, vcc, s53, v74
	s_mov_b32 s55, 0x2e000
	s_nop 0
	v_addc_co_u32_e32 v9, vcc, 0, v75, vcc
	v_add_co_u32_e32 v10, vcc, s54, v74
	s_mov_b32 s57, 0x31000
	s_nop 0
	v_addc_co_u32_e32 v11, vcc, 0, v75, vcc
	v_add_co_u32_e32 v14, vcc, s55, v74
	s_mov_b32 s59, 0x34000
	s_nop 0
	v_addc_co_u32_e32 v15, vcc, 0, v75, vcc
	v_add_co_u32_e32 v16, vcc, s57, v74
	s_mov_b32 s65, 0x37000
	s_nop 0
	v_addc_co_u32_e32 v17, vcc, 0, v75, vcc
	global_load_dwordx2 v[42:43], v[8:9], off offset:1024
	global_load_dwordx2 v[40:41], v[10:11], off
	global_load_dwordx2 v[38:39], v[14:15], off offset:3072
	global_load_dwordx2 v[36:37], v[16:17], off offset:2048
	v_add_co_u32_e32 v8, vcc, s59, v74
	s_mov_b32 s83, 0x39000
	s_nop 0
	v_addc_co_u32_e32 v9, vcc, 0, v75, vcc
	v_add_co_u32_e32 v10, vcc, s65, v74
	s_mov_b32 s37, 0x3c000
	s_nop 0
	v_addc_co_u32_e32 v11, vcc, 0, v75, vcc
	v_add_co_u32_e32 v14, vcc, s83, v74
	s_mov_b32 s94, 0x3f000
	s_nop 0
	v_addc_co_u32_e32 v15, vcc, 0, v75, vcc
	v_add_co_u32_e32 v16, vcc, s37, v74
	s_mov_b32 s56, 0x42000
	s_nop 0
	v_addc_co_u32_e32 v17, vcc, 0, v75, vcc
	global_load_dwordx2 v[34:35], v[8:9], off offset:1024
	global_load_dwordx2 v[32:33], v[10:11], off
	global_load_dwordx2 v[30:31], v[14:15], off offset:3072
	global_load_dwordx2 v[28:29], v[16:17], off offset:2048
	v_add_co_u32_e32 v8, vcc, s94, v74
	s_mov_b32 s84, 0x44000
	s_nop 0
	v_addc_co_u32_e32 v9, vcc, 0, v75, vcc
	v_add_co_u32_e32 v10, vcc, s56, v74
	s_mov_b32 s44, 0x47000
	s_nop 0
	v_addc_co_u32_e32 v11, vcc, 0, v75, vcc
	v_add_co_u32_e32 v14, vcc, s84, v74
	s_mov_b32 s85, 0x4a000
	s_nop 0
	v_addc_co_u32_e32 v15, vcc, 0, v75, vcc
	v_add_co_u32_e32 v16, vcc, s44, v74
	s_mov_b32 s90, 0x4d000
	s_nop 0
	v_addc_co_u32_e32 v17, vcc, 0, v75, vcc
	global_load_dwordx2 v[26:27], v[8:9], off offset:1024
	global_load_dwordx2 v[24:25], v[10:11], off
	global_load_dwordx2 v[22:23], v[14:15], off offset:3072
	global_load_dwordx2 v[18:19], v[16:17], off offset:2048
	v_add_co_u32_e32 v8, vcc, s85, v74
	s_mov_b32 s36, 0x4f000
	s_nop 0
	v_addc_co_u32_e32 v9, vcc, 0, v75, vcc
	v_add_co_u32_e32 v10, vcc, s90, v74
	s_mov_b32 s91, 0x52000
	s_nop 0
	v_addc_co_u32_e32 v11, vcc, 0, v75, vcc
	v_add_co_u32_e32 v14, vcc, s36, v74
	s_mov_b32 s86, 0x55000
	s_nop 0
	v_addc_co_u32_e32 v15, vcc, 0, v75, vcc
	v_add_co_u32_e32 v80, vcc, s91, v74
	s_nop 1
	v_addc_co_u32_e32 v81, vcc, 0, v75, vcc
	global_load_dwordx2 v[20:21], v[8:9], off offset:1024
	global_load_dwordx2 v[16:17], v[10:11], off
	s_nop 0
	global_load_dwordx2 v[14:15], v[14:15], off offset:3072
	s_nop 0
	global_load_dwordx2 v[10:11], v[80:81], off offset:2048
	v_add_co_u32_e32 v8, vcc, s86, v74
	s_nop 1
	v_addc_co_u32_e32 v9, vcc, 0, v75, vcc
	global_load_dwordx2 v[8:9], v[8:9], off offset:1024
	s_waitcnt vmcnt(31)
; #define LRU_STEP(h, l, x) do { const float a_ = fast_exp2(l); h = fmaf(a_, h, __builtin_amdgcn_sqrtf(fmaxf(fmaf(-a_, a_, 1.f), 0.f)) * (x)); } while (0)
; __global__ void __launch_bounds__(NTHREADS, 2) mega(Args args) {
;     ...
;                       float h0 = hc.x, h1 = hc.y;
; #pragma unroll
;                       for (int t = 0; t < 32; ++t) { LRU_STEP(h0, bf_lo(lb[t].x), bf_hi(lb[t].x)); LRU_STEP(h1, bf_lo(lb[t].y), bf_hi(lb[t].y)); hf0[t] = h0; hf1[t] = h1; } }
;                     { u32x2 lb[32]; unsigned gwv[32]; const f32x2 hc = *(const f32x2*)(CARRY + c1);
;                       const unsigned* l1p = LB + (size_t)M * LW + ro;
; #pragma unroll
;                       for (int t = 0; t < 32; ++t) { lb[t] = *(const u32x2*)(l1p + (size_t)t * LW); gwv[t] = *(const unsigned*)(GU + (size_t)(rbase + t) * (2 * LW) + ch); }
	v_lshlrev_b32_e32 v73, 16, v78
	v_exp_f32_e32 v73, v73
	v_and_b32_e32 v75, 0xffff0000, v78
	s_add_i32 s11, s11, 0x318000
	s_mul_hi_i32 s3, s10, 0x2c00
	v_fma_f32 v74, -v73, v73, 1.0
	v_max_f32_e32 v74, 0, v74
	v_sqrt_f32_e32 v74, v74
	s_add_u32 s4, s15, s11
	s_addc_u32 s5, s18, s3
	v_lshl_add_u64 v[6:7], s[4:5], 0, v[6:7]
	v_mul_f32_e32 v74, v74, v75
	v_fmac_f32_e32 v74, v73, v76
	v_lshlrev_b32_e32 v73, 16, v79
	v_exp_f32_e32 v75, v73
	v_and_b32_e32 v76, 0xffff0000, v79
	s_add_i32 s3, s20, 1
	v_fma_f32 v73, -v75, v75, 1.0
	v_max_f32_e32 v73, 0, v73
	v_sqrt_f32_e32 v73, v73
	s_nop 0
	v_mul_f32_e32 v73, v73, v76
	v_fmac_f32_e32 v73, v75, v77
	s_waitcnt vmcnt(30)
	v_lshlrev_b32_e32 v75, 16, v70
	v_exp_f32_e32 v75, v75
	v_and_b32_e32 v70, 0xffff0000, v70
	v_fma_f32 v76, -v75, v75, 1.0
	v_max_f32_e32 v76, 0, v76
	v_sqrt_f32_e32 v76, v76
	s_nop 0
	v_mul_f32_e32 v76, v76, v70
	v_lshlrev_b32_e32 v70, 16, v71
	v_exp_f32_e32 v70, v70
	v_fmac_f32_e32 v76, v75, v74
	v_and_b32_e32 v71, 0xffff0000, v71
	v_fma_f32 v75, -v70, v70, 1.0
	v_max_f32_e32 v75, 0, v75
	v_sqrt_f32_e32 v75, v75
	s_nop 0
	v_mul_f32_e32 v75, v75, v71
	v_fmac_f32_e32 v75, v70, v73
	s_waitcnt vmcnt(29)
	v_lshlrev_b32_e32 v70, 16, v68
	v_exp_f32_e32 v70, v70
	v_and_b32_e32 v68, 0xffff0000, v68
	v_fma_f32 v71, -v70, v70, 1.0
	v_max_f32_e32 v71, 0, v71
	v_sqrt_f32_e32 v71, v71
	s_nop 0
	v_mul_f32_e32 v78, v71, v68
	v_lshlrev_b32_e32 v68, 16, v69
	v_exp_f32_e32 v68, v68
	v_fmac_f32_e32 v78, v70, v76
	v_and_b32_e32 v69, 0xffff0000, v69
	v_fma_f32 v70, -v68, v68, 1.0
	v_max_f32_e32 v70, 0, v70
	v_sqrt_f32_e32 v70, v70
	s_nop 0
	v_mul_f32_e32 v77, v70, v69
	v_fmac_f32_e32 v77, v68, v75
	s_waitcnt vmcnt(28)
	v_lshlrev_b32_e32 v68, 16, v66
	v_exp_f32_e32 v68, v68
	v_and_b32_e32 v66, 0xffff0000, v66
	v_lshl_add_u64 v[70:71], s[42:43], 0, v[4:5]
	v_fma_f32 v69, -v68, v68, 1.0
	v_max_f32_e32 v69, 0, v69
	v_sqrt_f32_e32 v69, v69
	s_nop 0
	v_mul_f32_e32 v80, v69, v66
	v_lshlrev_b32_e32 v66, 16, v67
	v_exp_f32_e32 v66, v66
	v_fmac_f32_e32 v80, v68, v78
	v_and_b32_e32 v67, 0xffff0000, v67
	v_fma_f32 v68, -v66, v66, 1.0
	v_max_f32_e32 v68, 0, v68
	v_sqrt_f32_e32 v68, v68
	s_nop 0
	v_mul_f32_e32 v79, v68, v67
	v_fmac_f32_e32 v79, v66, v77
	s_waitcnt vmcnt(27)
	v_lshlrev_b32_e32 v66, 16, v64
	v_exp_f32_e32 v66, v66
	v_and_b32_e32 v64, 0xffff0000, v64
	v_lshl_add_u64 v[68:69], v[2:3], 1, s[38:39]
	v_mad_i64_i32 v[4:5], s[4:5], s20, v245, v[68:69]
	v_fma_f32 v67, -v66, v66, 1.0
	v_max_f32_e32 v67, 0, v67
	v_sqrt_f32_e32 v67, v67
	global_load_dwordx2 v[2:3], v[70:71], off
	global_load_dword v93, v[4:5], off
	v_add_co_u32_e32 v4, vcc, s9, v70
	v_mul_f32_e32 v82, v67, v64
	v_lshlrev_b32_e32 v64, 16, v65
	v_exp_f32_e32 v64, v64
	v_fmac_f32_e32 v82, v66, v80
	v_and_b32_e32 v65, 0xffff0000, v65
	v_addc_co_u32_e32 v5, vcc, 0, v71, vcc
	v_fma_f32 v66, -v64, v64, 1.0
	v_max_f32_e32 v66, 0, v66
	v_sqrt_f32_e32 v66, v66
	global_load_dwordx2 v[4:5], v[4:5], off offset:3072
	v_mul_f32_e32 v81, v66, v65
	v_fmac_f32_e32 v81, v64, v79
	s_waitcnt vmcnt(29)
	v_lshlrev_b32_e32 v64, 16, v62
	v_exp_f32_e32 v64, v64
	v_and_b32_e32 v62, 0xffff0000, v62
	v_fma_f32 v65, -v64, v64, 1.0
	v_max_f32_e32 v65, 0, v65
	v_sqrt_f32_e32 v65, v65
	s_nop 0
	v_mul_f32_e32 v84, v65, v62
	v_lshlrev_b32_e32 v62, 16, v63
	v_exp_f32_e32 v62, v62
	v_fmac_f32_e32 v84, v64, v82
	v_and_b32_e32 v63, 0xffff0000, v63
	v_fma_f32 v64, -v62, v62, 1.0
	v_max_f32_e32 v64, 0, v64
	v_sqrt_f32_e32 v64, v64
	s_nop 0
	v_mul_f32_e32 v83, v64, v63
	v_fmac_f32_e32 v83, v62, v81
	s_waitcnt vmcnt(28)
	v_lshlrev_b32_e32 v62, 16, v60
	v_exp_f32_e32 v62, v62
	v_and_b32_e32 v60, 0xffff0000, v60
	v_fma_f32 v63, -v62, v62, 1.0
	v_max_f32_e32 v63, 0, v63
	v_sqrt_f32_e32 v63, v63
	s_nop 0
	v_mul_f32_e32 v86, v63, v60
	v_lshlrev_b32_e32 v60, 16, v61
	v_exp_f32_e32 v60, v60
	v_fmac_f32_e32 v86, v62, v84
	v_and_b32_e32 v61, 0xffff0000, v61
	v_fma_f32 v62, -v60, v60, 1.0
	v_max_f32_e32 v62, 0, v62
	v_sqrt_f32_e32 v62, v62
	s_nop 0
	v_mul_f32_e32 v85, v62, v61
	v_fmac_f32_e32 v85, v60, v83
	s_waitcnt vmcnt(27)
	v_lshlrev_b32_e32 v60, 16, v58
	v_exp_f32_e32 v60, v60
	v_and_b32_e32 v58, 0xffff0000, v58
	v_fma_f32 v61, -v60, v60, 1.0
	v_max_f32_e32 v61, 0, v61
	v_sqrt_f32_e32 v61, v61
	s_nop 0
	v_mul_f32_e32 v88, v61, v58
	v_lshlrev_b32_e32 v58, 16, v59
	v_exp_f32_e32 v58, v58
	v_fmac_f32_e32 v88, v60, v86
	v_and_b32_e32 v59, 0xffff0000, v59
	v_fma_f32 v60, -v58, v58, 1.0
	v_max_f32_e32 v60, 0, v60
	v_sqrt_f32_e32 v60, v60
	s_nop 0
	v_mul_f32_e32 v87, v60, v59
	v_fmac_f32_e32 v87, v58, v85
	s_waitcnt vmcnt(26)
	v_lshlrev_b32_e32 v58, 16, v56
	v_exp_f32_e32 v58, v58
	v_and_b32_e32 v56, 0xffff0000, v56
	global_load_dwordx2 v[60:61], v[6:7], off
	v_mad_i64_i32 v[6:7], s[4:5], s3, v245, v[68:69]
	v_fma_f32 v59, -v58, v58, 1.0
	v_max_f32_e32 v59, 0, v59
	v_sqrt_f32_e32 v59, v59
	s_add_i32 s3, s20, 2
	global_load_dword v96, v[6:7], off
	v_mul_f32_e32 v90, v59, v56
	v_lshlrev_b32_e32 v56, 16, v57
	v_exp_f32_e32 v56, v56
	v_fmac_f32_e32 v90, v58, v88
	v_and_b32_e32 v57, 0xffff0000, v57
	v_fma_f32 v58, -v56, v56, 1.0
	v_max_f32_e32 v58, 0, v58
	v_sqrt_f32_e32 v58, v58
	s_nop 0
	v_mul_f32_e32 v89, v58, v57
	v_fmac_f32_e32 v89, v56, v87
	s_waitcnt vmcnt(27)
	v_lshlrev_b32_e32 v56, 16, v54
	v_exp_f32_e32 v56, v56
	v_and_b32_e32 v54, 0xffff0000, v54
	v_fma_f32 v57, -v56, v56, 1.0
	v_max_f32_e32 v57, 0, v57
	v_sqrt_f32_e32 v57, v57
	s_nop 0
	v_mul_f32_e32 v92, v57, v54
	v_lshlrev_b32_e32 v54, 16, v55
	v_exp_f32_e32 v54, v54
	v_fmac_f32_e32 v92, v56, v90
	v_and_b32_e32 v55, 0xffff0000, v55
	v_fma_f32 v56, -v54, v54, 1.0
	v_max_f32_e32 v56, 0, v56
	v_sqrt_f32_e32 v56, v56
	s_nop 0
	v_mul_f32_e32 v91, v56, v55
	v_fmac_f32_e32 v91, v54, v89
	s_waitcnt vmcnt(26)
; #define LRU_STEP(h, l, x) do { const float a_ = fast_exp2(l); h = fmaf(a_, h, __builtin_amdgcn_sqrtf(fmaxf(fmaf(-a_, a_, 1.f), 0.f)) * (x)); } while (0)
; __global__ void __launch_bounds__(NTHREADS, 2) mega(Args args) {
;     ...
;                     { u32x2 lb[32]; const f32x2 hc = *(const f32x2*)(CARRY + c0);
; #pragma unroll
;                       for (int t = 0; t < 32; ++t) lb[t] = *(const u32x2*)(LB + ro + (size_t)t * LW);
;                       __builtin_amdgcn_sched_barrier(0);
;                       float h0 = hc.x, h1 = hc.y;
; #pragma unroll
;                       for (int t = 0; t < 32; ++t) { LRU_STEP(h0, bf_lo(lb[t].x), bf_hi(lb[t].x)); LRU_STEP(h1, bf_lo(lb[t].y), bf_hi(lb[t].y)); hf0[t] = h0; hf1[t] = h1; } }
	v_lshlrev_b32_e32 v54, 16, v52
	v_exp_f32_e32 v54, v54
	v_and_b32_e32 v52, 0xffff0000, v52
	v_fma_f32 v55, -v54, v54, 1.0
	v_max_f32_e32 v55, 0, v55
	v_sqrt_f32_e32 v55, v55
	s_nop 0
	v_mul_f32_e32 v95, v55, v52
	v_lshlrev_b32_e32 v52, 16, v53
	v_exp_f32_e32 v52, v52
	v_fmac_f32_e32 v95, v54, v92
	v_and_b32_e32 v53, 0xffff0000, v53
	v_fma_f32 v54, -v52, v52, 1.0
	v_max_f32_e32 v54, 0, v54
	v_sqrt_f32_e32 v54, v54
	s_nop 0
	v_mul_f32_e32 v94, v54, v53
	v_fmac_f32_e32 v94, v52, v91
	s_waitcnt vmcnt(25)
	v_lshlrev_b32_e32 v52, 16, v50
	v_exp_f32_e32 v52, v52
	v_and_b32_e32 v50, 0xffff0000, v50
	v_fma_f32 v53, -v52, v52, 1.0
	v_max_f32_e32 v53, 0, v53
	v_sqrt_f32_e32 v53, v53
	s_nop 0
	v_mul_f32_e32 v98, v53, v50
	v_lshlrev_b32_e32 v50, 16, v51
	v_exp_f32_e32 v50, v50
	v_fmac_f32_e32 v98, v52, v95
	v_and_b32_e32 v51, 0xffff0000, v51
	v_fma_f32 v52, -v50, v50, 1.0
	v_max_f32_e32 v52, 0, v52
	v_sqrt_f32_e32 v52, v52
	s_nop 0
	v_mul_f32_e32 v97, v52, v51
	v_fmac_f32_e32 v97, v50, v94
	s_waitcnt vmcnt(24)
	v_lshlrev_b32_e32 v50, 16, v48
	v_exp_f32_e32 v50, v50
	v_and_b32_e32 v48, 0xffff0000, v48
	v_fma_f32 v51, -v50, v50, 1.0
	v_max_f32_e32 v51, 0, v51
	v_sqrt_f32_e32 v51, v51
	s_nop 0
	v_mul_f32_e32 v102, v51, v48
	v_lshlrev_b32_e32 v48, 16, v49
	v_exp_f32_e32 v48, v48
	v_fmac_f32_e32 v102, v50, v98
	v_and_b32_e32 v49, 0xffff0000, v49
	v_fma_f32 v50, -v48, v48, 1.0
	v_max_f32_e32 v50, 0, v50
	v_sqrt_f32_e32 v50, v50
	s_nop 0
	v_mul_f32_e32 v100, v50, v49
	v_fmac_f32_e32 v100, v48, v97
	s_waitcnt vmcnt(23)
	v_lshlrev_b32_e32 v48, 16, v46
	v_exp_f32_e32 v48, v48
	v_and_b32_e32 v46, 0xffff0000, v46
	v_fma_f32 v49, -v48, v48, 1.0
	v_max_f32_e32 v49, 0, v49
	v_sqrt_f32_e32 v49, v49
	s_nop 0
	v_mul_f32_e32 v105, v49, v46
	v_lshlrev_b32_e32 v46, 16, v47
	v_exp_f32_e32 v46, v46
	v_fmac_f32_e32 v105, v48, v102
	v_and_b32_e32 v47, 0xffff0000, v47
	v_fma_f32 v48, -v46, v46, 1.0
	v_max_f32_e32 v48, 0, v48
	v_sqrt_f32_e32 v48, v48
	s_nop 0
	v_mul_f32_e32 v104, v48, v47
	v_fmac_f32_e32 v104, v46, v100
	s_waitcnt vmcnt(22)
	v_lshlrev_b32_e32 v46, 16, v44
	v_exp_f32_e32 v46, v46
	v_and_b32_e32 v44, 0xffff0000, v44
	v_fma_f32 v47, -v46, v46, 1.0
	v_max_f32_e32 v47, 0, v47
	v_sqrt_f32_e32 v47, v47
	s_nop 0
	v_mul_f32_e32 v108, v47, v44
	v_lshlrev_b32_e32 v44, 16, v45
	v_exp_f32_e32 v44, v44
	v_fmac_f32_e32 v108, v46, v105
	v_and_b32_e32 v45, 0xffff0000, v45
	v_fma_f32 v46, -v44, v44, 1.0
	v_max_f32_e32 v46, 0, v46
	v_sqrt_f32_e32 v46, v46
	s_nop 0
	v_mul_f32_e32 v107, v46, v45
	v_fmac_f32_e32 v107, v44, v104
	s_waitcnt vmcnt(21)
	v_lshlrev_b32_e32 v44, 16, v42
	v_exp_f32_e32 v44, v44
	v_and_b32_e32 v42, 0xffff0000, v42
	v_fma_f32 v45, -v44, v44, 1.0
	v_max_f32_e32 v45, 0, v45
	v_sqrt_f32_e32 v45, v45
	s_nop 0
	v_mul_f32_e32 v111, v45, v42
	v_lshlrev_b32_e32 v42, 16, v43
	v_exp_f32_e32 v42, v42
	v_fmac_f32_e32 v111, v44, v108
	v_and_b32_e32 v43, 0xffff0000, v43
	v_fma_f32 v44, -v42, v42, 1.0
	v_max_f32_e32 v44, 0, v44
	v_sqrt_f32_e32 v44, v44
	s_nop 0
	v_mul_f32_e32 v110, v44, v43
	v_fmac_f32_e32 v110, v42, v107
	s_waitcnt vmcnt(20)
	v_lshlrev_b32_e32 v42, 16, v40
	v_exp_f32_e32 v42, v42
	v_and_b32_e32 v40, 0xffff0000, v40
	v_fma_f32 v43, -v42, v42, 1.0
	v_max_f32_e32 v43, 0, v43
	v_sqrt_f32_e32 v43, v43
	s_nop 0
	v_mul_f32_e32 v115, v43, v40
	v_lshlrev_b32_e32 v40, 16, v41
	v_exp_f32_e32 v40, v40
	v_fmac_f32_e32 v115, v42, v111
	v_and_b32_e32 v41, 0xffff0000, v41
	v_fma_f32 v42, -v40, v40, 1.0
	v_max_f32_e32 v42, 0, v42
	v_sqrt_f32_e32 v42, v42
	s_nop 0
	v_mul_f32_e32 v114, v42, v41
	v_fmac_f32_e32 v114, v40, v110
	s_waitcnt vmcnt(19)
	v_lshlrev_b32_e32 v40, 16, v38
	v_exp_f32_e32 v40, v40
	v_and_b32_e32 v38, 0xffff0000, v38
	v_fma_f32 v41, -v40, v40, 1.0
	v_max_f32_e32 v41, 0, v41
	v_sqrt_f32_e32 v41, v41
	s_nop 0
	v_mul_f32_e32 v118, v41, v38
	v_lshlrev_b32_e32 v38, 16, v39
	v_exp_f32_e32 v38, v38
	v_fmac_f32_e32 v118, v40, v115
	v_and_b32_e32 v39, 0xffff0000, v39
	v_fma_f32 v40, -v38, v38, 1.0
	v_max_f32_e32 v40, 0, v40
	v_sqrt_f32_e32 v40, v40
	s_nop 0
	v_mul_f32_e32 v117, v40, v39
	v_fmac_f32_e32 v117, v38, v114
	s_waitcnt vmcnt(18)
	v_lshlrev_b32_e32 v38, 16, v36
	v_exp_f32_e32 v38, v38
	v_and_b32_e32 v36, 0xffff0000, v36
	v_fma_f32 v39, -v38, v38, 1.0
	v_max_f32_e32 v39, 0, v39
	v_sqrt_f32_e32 v39, v39
	s_nop 0
	v_mul_f32_e32 v121, v39, v36
	v_lshlrev_b32_e32 v36, 16, v37
	v_exp_f32_e32 v36, v36
	v_fmac_f32_e32 v121, v38, v118
	v_and_b32_e32 v37, 0xffff0000, v37
	v_fma_f32 v38, -v36, v36, 1.0
	v_max_f32_e32 v38, 0, v38
	v_sqrt_f32_e32 v38, v38
	s_nop 0
	v_mul_f32_e32 v120, v38, v37
	v_fmac_f32_e32 v120, v36, v117
	s_waitcnt vmcnt(17)
	v_lshlrev_b32_e32 v36, 16, v34
	v_exp_f32_e32 v36, v36
	v_and_b32_e32 v34, 0xffff0000, v34
	v_fma_f32 v37, -v36, v36, 1.0
	v_max_f32_e32 v37, 0, v37
	v_sqrt_f32_e32 v37, v37
	s_nop 0
	v_mul_f32_e32 v124, v37, v34
	v_lshlrev_b32_e32 v34, 16, v35
	v_exp_f32_e32 v34, v34
	v_fmac_f32_e32 v124, v36, v121
	v_and_b32_e32 v35, 0xffff0000, v35
	v_fma_f32 v36, -v34, v34, 1.0
	v_max_f32_e32 v36, 0, v36
	v_sqrt_f32_e32 v36, v36
	s_nop 0
	v_mul_f32_e32 v123, v36, v35
	v_fmac_f32_e32 v123, v34, v120
	s_waitcnt vmcnt(16)
	v_lshlrev_b32_e32 v34, 16, v32
	v_exp_f32_e32 v34, v34
	v_and_b32_e32 v32, 0xffff0000, v32
	v_fma_f32 v35, -v34, v34, 1.0
	v_max_f32_e32 v35, 0, v35
	v_sqrt_f32_e32 v35, v35
	s_nop 0
	v_mul_f32_e32 v128, v35, v32
	v_lshlrev_b32_e32 v32, 16, v33
	v_exp_f32_e32 v32, v32
	v_fmac_f32_e32 v128, v34, v124
	v_and_b32_e32 v33, 0xffff0000, v33
	v_fma_f32 v34, -v32, v32, 1.0
	v_max_f32_e32 v34, 0, v34
	v_sqrt_f32_e32 v34, v34
	s_nop 0
	v_mul_f32_e32 v127, v34, v33
	v_fmac_f32_e32 v127, v32, v123
	s_waitcnt vmcnt(15)
; #define LRU_STEP(h, l, x) do { const float a_ = fast_exp2(l); h = fmaf(a_, h, __builtin_amdgcn_sqrtf(fmaxf(fmaf(-a_, a_, 1.f), 0.f)) * (x)); } while (0)
; __global__ void __launch_bounds__(NTHREADS, 2) mega(Args args) {
;     ...
;                     { u32x2 lb[32]; const f32x2 hc = *(const f32x2*)(CARRY + c0);
; #pragma unroll
;                       for (int t = 0; t < 32; ++t) lb[t] = *(const u32x2*)(LB + ro + (size_t)t * LW);
;                       __builtin_amdgcn_sched_barrier(0);
;                       float h0 = hc.x, h1 = hc.y;
; #pragma unroll
;                       for (int t = 0; t < 32; ++t) { LRU_STEP(h0, bf_lo(lb[t].x), bf_hi(lb[t].x)); LRU_STEP(h1, bf_lo(lb[t].y), bf_hi(lb[t].y)); hf0[t] = h0; hf1[t] = h1; } }
	v_lshlrev_b32_e32 v32, 16, v30
	v_exp_f32_e32 v32, v32
	v_and_b32_e32 v30, 0xffff0000, v30
	v_fma_f32 v33, -v32, v32, 1.0
	v_max_f32_e32 v33, 0, v33
	v_sqrt_f32_e32 v33, v33
	s_nop 0
	v_mul_f32_e32 v131, v33, v30
	v_lshlrev_b32_e32 v30, 16, v31
	v_exp_f32_e32 v30, v30
	v_fmac_f32_e32 v131, v32, v128
	v_and_b32_e32 v31, 0xffff0000, v31
	v_fma_f32 v32, -v30, v30, 1.0
	v_max_f32_e32 v32, 0, v32
	v_sqrt_f32_e32 v32, v32
	s_nop 0
	v_mul_f32_e32 v130, v32, v31
	v_fmac_f32_e32 v130, v30, v127
	s_waitcnt vmcnt(14)
	v_lshlrev_b32_e32 v30, 16, v28
	v_exp_f32_e32 v30, v30
	v_and_b32_e32 v28, 0xffff0000, v28
	v_fma_f32 v31, -v30, v30, 1.0
	v_max_f32_e32 v31, 0, v31
	v_sqrt_f32_e32 v31, v31
	s_nop 0
	v_mul_f32_e32 v134, v31, v28
	v_lshlrev_b32_e32 v28, 16, v29
	v_exp_f32_e32 v28, v28
	v_fmac_f32_e32 v134, v30, v131
	v_and_b32_e32 v29, 0xffff0000, v29
	v_fma_f32 v30, -v28, v28, 1.0
	v_max_f32_e32 v30, 0, v30
	v_sqrt_f32_e32 v30, v30
	s_nop 0
	v_mul_f32_e32 v133, v30, v29
	v_fmac_f32_e32 v133, v28, v130
	s_waitcnt vmcnt(13)
	v_lshlrev_b32_e32 v28, 16, v26
	v_exp_f32_e32 v28, v28
	v_and_b32_e32 v26, 0xffff0000, v26
	v_fma_f32 v29, -v28, v28, 1.0
	v_max_f32_e32 v29, 0, v29
	v_sqrt_f32_e32 v29, v29
	s_nop 0
	v_mul_f32_e32 v138, v29, v26
	v_lshlrev_b32_e32 v26, 16, v27
	v_exp_f32_e32 v26, v26
	v_fmac_f32_e32 v138, v28, v134
	v_and_b32_e32 v27, 0xffff0000, v27
	v_fma_f32 v28, -v26, v26, 1.0
	v_max_f32_e32 v28, 0, v28
	v_sqrt_f32_e32 v28, v28
	s_nop 0
	v_mul_f32_e32 v136, v28, v27
	v_fmac_f32_e32 v136, v26, v133
	s_waitcnt vmcnt(12)
	v_lshlrev_b32_e32 v26, 16, v24
	v_exp_f32_e32 v26, v26
	v_and_b32_e32 v24, 0xffff0000, v24
	v_fma_f32 v27, -v26, v26, 1.0
	v_max_f32_e32 v27, 0, v27
	v_sqrt_f32_e32 v27, v27
	s_nop 0
	v_mul_f32_e32 v141, v27, v24
	v_lshlrev_b32_e32 v24, 16, v25
	v_exp_f32_e32 v24, v24
	v_fmac_f32_e32 v141, v26, v138
	v_and_b32_e32 v25, 0xffff0000, v25
	v_fma_f32 v26, -v24, v24, 1.0
	v_max_f32_e32 v26, 0, v26
	v_sqrt_f32_e32 v26, v26
	s_nop 0
	v_mul_f32_e32 v140, v26, v25
	v_fmac_f32_e32 v140, v24, v136
	s_waitcnt vmcnt(11)
	v_lshlrev_b32_e32 v24, 16, v22
	v_exp_f32_e32 v24, v24
	v_and_b32_e32 v22, 0xffff0000, v22
	v_fma_f32 v25, -v24, v24, 1.0
	v_max_f32_e32 v25, 0, v25
	v_sqrt_f32_e32 v25, v25
	s_nop 0
	v_mul_f32_e32 v144, v25, v22
	v_lshlrev_b32_e32 v22, 16, v23
	v_exp_f32_e32 v22, v22
	v_fmac_f32_e32 v144, v24, v141
	v_and_b32_e32 v23, 0xffff0000, v23
	v_fma_f32 v24, -v22, v22, 1.0
	v_max_f32_e32 v24, 0, v24
	v_sqrt_f32_e32 v24, v24
	s_nop 0
	v_mul_f32_e32 v143, v24, v23
	v_fmac_f32_e32 v143, v22, v140
	s_waitcnt vmcnt(10)
	v_lshlrev_b32_e32 v22, 16, v18
	v_exp_f32_e32 v22, v22
	v_and_b32_e32 v18, 0xffff0000, v18
	v_fma_f32 v23, -v22, v22, 1.0
	v_max_f32_e32 v23, 0, v23
	v_sqrt_f32_e32 v23, v23
	s_nop 0
	v_mul_f32_e32 v147, v23, v18
	v_lshlrev_b32_e32 v18, 16, v19
	v_exp_f32_e32 v18, v18
	v_fmac_f32_e32 v147, v22, v144
	v_and_b32_e32 v19, 0xffff0000, v19
	v_fma_f32 v22, -v18, v18, 1.0
	v_max_f32_e32 v22, 0, v22
	v_sqrt_f32_e32 v22, v22
	s_nop 0
	v_mul_f32_e32 v146, v22, v19
	v_fmac_f32_e32 v146, v18, v143
	s_waitcnt vmcnt(9)
	v_lshlrev_b32_e32 v18, 16, v20
	v_exp_f32_e32 v18, v18
	v_and_b32_e32 v20, 0xffff0000, v20
	v_fma_f32 v19, -v18, v18, 1.0
	v_max_f32_e32 v19, 0, v19
	v_sqrt_f32_e32 v19, v19
	s_nop 0
	v_mul_f32_e32 v151, v19, v20
	v_fmac_f32_e32 v151, v18, v147
	v_lshlrev_b32_e32 v18, 16, v21
	v_exp_f32_e32 v18, v18
	v_and_b32_e32 v20, 0xffff0000, v21
	v_fma_f32 v19, -v18, v18, 1.0
	v_max_f32_e32 v19, 0, v19
	v_sqrt_f32_e32 v19, v19
	s_nop 0
	v_mul_f32_e32 v149, v19, v20
	v_fmac_f32_e32 v149, v18, v146
	s_waitcnt vmcnt(8)
	v_lshlrev_b32_e32 v18, 16, v16
	v_exp_f32_e32 v18, v18
	v_and_b32_e32 v16, 0xffff0000, v16
	v_fma_f32 v19, -v18, v18, 1.0
	v_max_f32_e32 v19, 0, v19
	v_sqrt_f32_e32 v19, v19
	s_nop 0
	v_mul_f32_e32 v154, v19, v16
	v_lshlrev_b32_e32 v16, 16, v17
	v_exp_f32_e32 v16, v16
	v_fmac_f32_e32 v154, v18, v151
	v_and_b32_e32 v17, 0xffff0000, v17
	v_fma_f32 v18, -v16, v16, 1.0
	v_max_f32_e32 v18, 0, v18
	v_sqrt_f32_e32 v18, v18
	s_nop 0
	v_mul_f32_e32 v152, v18, v17
	v_fmac_f32_e32 v152, v16, v149
	s_waitcnt vmcnt(7)
	v_lshlrev_b32_e32 v16, 16, v14
	v_exp_f32_e32 v16, v16
	v_and_b32_e32 v14, 0xffff0000, v14
	v_fma_f32 v17, -v16, v16, 1.0
	v_max_f32_e32 v17, 0, v17
	v_sqrt_f32_e32 v17, v17
	s_nop 0
	v_mul_f32_e32 v157, v17, v14
	v_lshlrev_b32_e32 v14, 16, v15
	v_exp_f32_e32 v14, v14
	v_fmac_f32_e32 v157, v16, v154
	v_and_b32_e32 v15, 0xffff0000, v15
	v_fma_f32 v16, -v14, v14, 1.0
	v_max_f32_e32 v16, 0, v16
	v_sqrt_f32_e32 v16, v16
	s_nop 0
	v_mul_f32_e32 v155, v16, v15
	v_fmac_f32_e32 v155, v14, v152
	s_waitcnt vmcnt(6)
	v_lshlrev_b32_e32 v14, 16, v10
	v_exp_f32_e32 v14, v14
	v_and_b32_e32 v10, 0xffff0000, v10
	v_fma_f32 v15, -v14, v14, 1.0
	v_max_f32_e32 v15, 0, v15
	v_sqrt_f32_e32 v15, v15
	s_nop 0
	v_mul_f32_e32 v160, v15, v10
	v_lshlrev_b32_e32 v10, 16, v11
	v_exp_f32_e32 v10, v10
	v_fmac_f32_e32 v160, v14, v157
	v_and_b32_e32 v11, 0xffff0000, v11
	v_fma_f32 v14, -v10, v10, 1.0
	v_max_f32_e32 v14, 0, v14
	v_sqrt_f32_e32 v14, v14
	s_nop 0
	v_mul_f32_e32 v158, v14, v11
	v_fmac_f32_e32 v158, v10, v155
	s_waitcnt vmcnt(5)
; #define LRU_STEP(h, l, x) do { const float a_ = fast_exp2(l); h = fmaf(a_, h, __builtin_amdgcn_sqrtf(fmaxf(fmaf(-a_, a_, 1.f), 0.f)) * (x)); } while (0)
; __global__ void __launch_bounds__(NTHREADS, 2) mega(Args args) {
;     ...
;                       for (int t = 0; t < 32; ++t) { LRU_STEP(h0, bf_lo(lb[t].x), bf_hi(lb[t].x)); LRU_STEP(h1, bf_lo(lb[t].y), bf_hi(lb[t].y)); hf0[t] = h0; hf1[t] = h1; } }
;                     { u32x2 lb[32]; unsigned gwv[32]; const f32x2 hc = *(const f32x2*)(CARRY + c1);
;                       const unsigned* l1p = LB + (size_t)M * LW + ro;
; #pragma unroll
;                       for (int t = 0; t < 32; ++t) { lb[t] = *(const u32x2*)(l1p + (size_t)t * LW); gwv[t] = *(const unsigned*)(GU + (size_t)(rbase + t) * (2 * LW) + ch); }
	v_lshlrev_b32_e32 v10, 16, v8
	v_exp_f32_e32 v10, v10
	v_and_b32_e32 v8, 0xffff0000, v8
	v_fma_f32 v11, -v10, v10, 1.0
	v_max_f32_e32 v11, 0, v11
	v_sqrt_f32_e32 v11, v11
	s_nop 0
	v_mul_f32_e32 v163, v11, v8
	v_lshlrev_b32_e32 v8, 16, v9
	v_exp_f32_e32 v8, v8
	v_fmac_f32_e32 v163, v10, v160
	v_and_b32_e32 v9, 0xffff0000, v9
	v_fma_f32 v10, -v8, v8, 1.0
	v_max_f32_e32 v10, 0, v10
	v_sqrt_f32_e32 v10, v10
	s_nop 0
	v_mul_f32_e32 v161, v10, v9
	v_fmac_f32_e32 v161, v8, v158
	v_mad_i64_i32 v[8:9], s[4:5], s3, v245, v[68:69]
	s_add_i32 s3, s20, 3
	v_mad_i64_i32 v[10:11], s[4:5], s3, v245, v[68:69]
	s_add_i32 s3, s20, 4
	v_mad_i64_i32 v[14:15], s[4:5], s3, v245, v[68:69]
	s_add_i32 s3, s20, 5
	v_mad_i64_i32 v[16:17], s[4:5], s3, v245, v[68:69]
	s_add_i32 s3, s20, 6
	v_mad_i64_i32 v[18:19], s[4:5], s3, v245, v[68:69]
	s_add_i32 s3, s20, 7
	v_mad_i64_i32 v[20:21], s[4:5], s3, v245, v[68:69]
	global_load_dword v99, v[8:9], off
	global_load_dword v101, v[10:11], off
	global_load_dword v103, v[14:15], off
	global_load_dword v106, v[16:17], off
	global_load_dword v109, v[18:19], off
	global_load_dword v112, v[20:21], off
	v_add_co_u32_e32 v6, vcc, s25, v70
	s_add_i32 s3, s20, 8
	s_nop 0
	v_addc_co_u32_e32 v7, vcc, 0, v71, vcc
	v_add_co_u32_e32 v8, vcc, s22, v70
	v_mad_i64_i32 v[22:23], s[4:5], s3, v245, v[68:69]
	s_nop 0
	v_addc_co_u32_e32 v9, vcc, 0, v71, vcc
	v_add_co_u32_e32 v10, vcc, s24, v70
	s_add_i32 s3, s20, 9
	s_nop 0
	v_addc_co_u32_e32 v11, vcc, 0, v71, vcc
	v_add_co_u32_e32 v14, vcc, s30, v70
	v_mad_i64_i32 v[24:25], s[4:5], s3, v245, v[68:69]
	s_nop 0
	v_addc_co_u32_e32 v15, vcc, 0, v71, vcc
	v_add_co_u32_e32 v16, vcc, s16, v70
	s_add_i32 s3, s20, 10
	s_nop 0
	v_addc_co_u32_e32 v17, vcc, 0, v71, vcc
	v_add_co_u32_e32 v18, vcc, s31, v70
	v_mad_i64_i32 v[26:27], s[4:5], s3, v245, v[68:69]
	s_add_i32 s3, s20, 11
	v_addc_co_u32_e32 v19, vcc, 0, v71, vcc
	v_mad_i64_i32 v[28:29], s[4:5], s3, v245, v[68:69]
	s_add_i32 s3, s20, 12
	v_add_co_u32_e32 v20, vcc, s21, v70
	v_mad_i64_i32 v[30:31], s[4:5], s3, v245, v[68:69]
	s_add_i32 s3, s20, 13
	v_addc_co_u32_e32 v21, vcc, 0, v71, vcc
	v_mad_i64_i32 v[32:33], s[4:5], s3, v245, v[68:69]
	s_add_i32 s3, s20, 14
	global_load_dwordx2 v[16:17], v[16:17], off offset:2048
	v_mad_i64_i32 v[34:35], s[4:5], s3, v245, v[68:69]
	global_load_dwordx2 v[18:19], v[18:19], off offset:1024
	s_add_i32 s3, s20, 15
	global_load_dwordx2 v[20:21], v[20:21], off
	v_mad_i64_i32 v[36:37], s[4:5], s3, v245, v[68:69]
	global_load_dword v113, v[22:23], off
	v_add_co_u32_e32 v22, vcc, s33, v70
	global_load_dword v116, v[24:25], off
	global_load_dword v119, v[26:27], off
	global_load_dword v122, v[28:29], off
	global_load_dword v125, v[30:31], off
	global_load_dword v126, v[32:33], off
	global_load_dword v129, v[34:35], off
	global_load_dword v132, v[36:37], off
	v_addc_co_u32_e32 v23, vcc, 0, v71, vcc
	global_load_dwordx2 v[22:23], v[22:23], off offset:3072
	v_add_co_u32_e32 v24, vcc, s34, v70
	s_add_i32 s3, s20, 16
	s_nop 0
	v_addc_co_u32_e32 v25, vcc, 0, v71, vcc
	v_add_co_u32_e32 v26, vcc, s23, v70
	v_mad_i64_i32 v[38:39], s[4:5], s3, v245, v[68:69]
	s_nop 0
	v_addc_co_u32_e32 v27, vcc, 0, v71, vcc
	v_add_co_u32_e32 v28, vcc, s35, v70
	s_add_i32 s3, s20, 17
	s_nop 0
	v_addc_co_u32_e32 v29, vcc, 0, v71, vcc
	v_add_co_u32_e32 v30, vcc, s48, v70
	v_mad_i64_i32 v[40:41], s[4:5], s3, v245, v[68:69]
	s_nop 0
	v_addc_co_u32_e32 v31, vcc, 0, v71, vcc
	v_add_co_u32_e32 v32, vcc, s52, v70
	s_add_i32 s3, s20, 18
	s_nop 0
	v_addc_co_u32_e32 v33, vcc, 0, v71, vcc
	v_add_co_u32_e32 v34, vcc, s53, v70
	v_mad_i64_i32 v[42:43], s[4:5], s3, v245, v[68:69]
	s_add_i32 s3, s20, 19
	v_addc_co_u32_e32 v35, vcc, 0, v71, vcc
	v_mad_i64_i32 v[44:45], s[4:5], s3, v245, v[68:69]
	s_add_i32 s3, s20, 20
	v_add_co_u32_e32 v36, vcc, s54, v70
	v_mad_i64_i32 v[46:47], s[4:5], s3, v245, v[68:69]
	s_add_i32 s3, s20, 21
	v_addc_co_u32_e32 v37, vcc, 0, v71, vcc
	v_mad_i64_i32 v[48:49], s[4:5], s3, v245, v[68:69]
	s_add_i32 s3, s20, 22
	global_load_dwordx2 v[32:33], v[32:33], off offset:2048
	v_mad_i64_i32 v[50:51], s[4:5], s3, v245, v[68:69]
	global_load_dwordx2 v[34:35], v[34:35], off offset:1024
	s_add_i32 s3, s20, 23
	global_load_dwordx2 v[36:37], v[36:37], off
	v_mad_i64_i32 v[52:53], s[4:5], s3, v245, v[68:69]
	global_load_dword v135, v[38:39], off
	v_add_co_u32_e32 v38, vcc, s55, v70
	global_load_dword v137, v[40:41], off
	global_load_dword v139, v[42:43], off
	global_load_dword v142, v[44:45], off
	global_load_dword v145, v[46:47], off
	global_load_dword v148, v[48:49], off
	global_load_dword v150, v[50:51], off
	global_load_dword v153, v[52:53], off
	v_addc_co_u32_e32 v39, vcc, 0, v71, vcc
	global_load_dwordx2 v[38:39], v[38:39], off offset:3072
	v_add_co_u32_e32 v40, vcc, s57, v70
	s_add_i32 s3, s20, 24
	s_nop 0
	v_addc_co_u32_e32 v41, vcc, 0, v71, vcc
	v_add_co_u32_e32 v42, vcc, s59, v70
	v_mad_i64_i32 v[54:55], s[4:5], s3, v245, v[68:69]
	s_nop 0
	v_addc_co_u32_e32 v43, vcc, 0, v71, vcc
	v_add_co_u32_e32 v44, vcc, s65, v70
	s_add_i32 s3, s20, 25
	s_nop 0
	v_addc_co_u32_e32 v45, vcc, 0, v71, vcc
	v_add_co_u32_e32 v46, vcc, s83, v70
	v_mad_i64_i32 v[56:57], s[4:5], s3, v245, v[68:69]
	s_nop 0
	v_addc_co_u32_e32 v47, vcc, 0, v71, vcc
	v_add_co_u32_e32 v48, vcc, s37, v70
	s_add_i32 s3, s20, 26
	s_nop 0
	v_addc_co_u32_e32 v49, vcc, 0, v71, vcc
	v_add_co_u32_e32 v50, vcc, s94, v70
	v_mad_i64_i32 v[58:59], s[4:5], s3, v245, v[68:69]
	s_add_i32 s3, s20, 27
	v_addc_co_u32_e32 v51, vcc, 0, v71, vcc
	v_mad_i64_i32 v[62:63], s[4:5], s3, v245, v[68:69]
	s_add_i32 s3, s20, 28
	v_add_co_u32_e32 v52, vcc, s56, v70
	v_mad_i64_i32 v[64:65], s[4:5], s3, v245, v[68:69]
; __device__ __forceinline__ unsigned pk2(float lo, float hi) { return f2bf(lo) | (f2bf(hi) << 16); }
; __device__ __forceinline__ float fast_sigmoid(float x) { return fast_rcp(1.f + fast_exp2(-1.4426950408889634f * x)); }
; #define LRU_STEP(h, l, x) do { const float a_ = fast_exp2(l); h = fmaf(a_, h, __builtin_amdgcn_sqrtf(fmaxf(fmaf(-a_, a_, 1.f), 0.f)) * (x)); } while (0)
; __global__ void __launch_bounds__(NTHREADS, 2) mega(Args args) {
;     ...
;                     { u32x2 lb[32]; unsigned gwv[32]; const f32x2 hc = *(const f32x2*)(CARRY + c1);
;                       const unsigned* l1p = LB + (size_t)M * LW + ro;
; #pragma unroll
;                       for (int t = 0; t < 32; ++t) { lb[t] = *(const u32x2*)(l1p + (size_t)t * LW); gwv[t] = *(const unsigned*)(GU + (size_t)(rbase + t) * (2 * LW) + ch); }
;                       __builtin_amdgcn_sched_barrier(0);
;                       float h0 = hc.x, h1 = hc.y;
; #pragma unroll
;                       for (int t = 31; t >= 0; --t) { LRU_STEP(h0, bf_lo(lb[t].x), bf_hi(lb[t].x)); LRU_STEP(h1, bf_lo(lb[t].y), bf_hi(lb[t].y));
;                           const float g0 = bf_lo(gwv[t]), g1 = bf_hi(gwv[t]);
;                           const float z0 = g0 * fast_sigmoid(1.5957691216057308f * (g0 + 0.044715f * g0 * g0 * g0)) * (hf0[t] + h0);
;                           const float z1 = g1 * fast_sigmoid(1.5957691216057308f * (g1 + 0.044715f * g1 * g1 * g1)) * (hf1[t] + h1);
;                           *(unsigned*)(Zb + ro + (size_t)t * LW) = pk2(z0, z1); } }
	s_add_i32 s3, s20, 29
	v_addc_co_u32_e32 v53, vcc, 0, v71, vcc
	v_mad_i64_i32 v[66:67], s[4:5], s3, v245, v[68:69]
	s_add_i32 s3, s20, 30
	global_load_dwordx2 v[48:49], v[48:49], off offset:2048
	v_mad_i64_i32 v[168:169], s[4:5], s3, v245, v[68:69]
	global_load_dwordx2 v[50:51], v[50:51], off offset:1024
	s_add_i32 s3, s20, 31
	global_load_dwordx2 v[52:53], v[52:53], off
	v_mad_i64_i32 v[68:69], s[4:5], s3, v245, v[68:69]
	global_load_dword v156, v[54:55], off
	v_add_co_u32_e32 v54, vcc, s84, v70
	global_load_dword v159, v[56:57], off
	global_load_dword v162, v[58:59], off
	global_load_dword v164, v[62:63], off
	global_load_dword v165, v[64:65], off
	global_load_dword v166, v[66:67], off
	global_load_dword v167, v[168:169], off
	v_addc_co_u32_e32 v55, vcc, 0, v71, vcc
	global_load_dwordx2 v[54:55], v[54:55], off offset:3072
	s_nop 0
	global_load_dword v68, v[68:69], off
	v_add_co_u32_e32 v56, vcc, s44, v70
	global_load_dwordx2 v[6:7], v[6:7], off offset:2048
	s_nop 0
	v_addc_co_u32_e32 v57, vcc, 0, v71, vcc
	v_add_co_u32_e32 v58, vcc, s85, v70
	global_load_dwordx2 v[8:9], v[8:9], off offset:1024
	s_nop 0
	v_addc_co_u32_e32 v59, vcc, 0, v71, vcc
	v_add_co_u32_e32 v62, vcc, s90, v70
	global_load_dwordx2 v[10:11], v[10:11], off
	s_nop 0
	v_addc_co_u32_e32 v63, vcc, 0, v71, vcc
	v_add_co_u32_e32 v64, vcc, s36, v70
	global_load_dwordx2 v[14:15], v[14:15], off offset:3072
	s_nop 0
	v_addc_co_u32_e32 v65, vcc, 0, v71, vcc
	v_add_co_u32_e32 v66, vcc, s91, v70
	global_load_dwordx2 v[24:25], v[24:25], off offset:2048
	s_nop 0
	v_addc_co_u32_e32 v67, vcc, 0, v71, vcc
	v_add_co_u32_e32 v70, vcc, s86, v70
	global_load_dwordx2 v[26:27], v[26:27], off offset:1024
	s_nop 0
	v_addc_co_u32_e32 v71, vcc, 0, v71, vcc
	global_load_dwordx2 v[28:29], v[28:29], off
	s_nop 0
	global_load_dwordx2 v[30:31], v[30:31], off offset:3072
	s_nop 0
	global_load_dwordx2 v[40:41], v[40:41], off offset:2048
	s_nop 0
	global_load_dwordx2 v[42:43], v[42:43], off offset:1024
	s_nop 0
	global_load_dwordx2 v[44:45], v[44:45], off
	s_nop 0
	global_load_dwordx2 v[46:47], v[46:47], off offset:3072
	s_nop 0
	global_load_dwordx2 v[56:57], v[56:57], off offset:2048
	s_nop 0
	global_load_dwordx2 v[58:59], v[58:59], off offset:1024
	s_nop 0
	global_load_dwordx2 v[62:63], v[62:63], off
	s_nop 0
	global_load_dwordx2 v[64:65], v[64:65], off offset:3072
	s_nop 0
	global_load_dwordx2 v[66:67], v[66:67], off offset:2048
	s_nop 0
	global_load_dwordx2 v[70:71], v[70:71], off offset:1024
	s_waitcnt vmcnt(0)
	v_lshlrev_b32_e32 v69, 16, v70
	v_exp_f32_e32 v69, v69
	v_and_b32_e32 v70, 0xffff0000, v70
	v_lshl_add_u64 v[12:13], v[12:13], 1, s[40:41]
	s_mov_b32 s3, 0x2a000
	v_fma_f32 v168, -v69, v69, 1.0
	v_max_f32_e32 v168, 0, v168
	v_sqrt_f32_e32 v168, v168
	v_readlane_b32 s4, v255, 9
	s_add_i32 s14, s14, s4
	v_subrev_u32_e32 v72, s19, v72
	v_mul_f32_e32 v70, v168, v70
	v_fmac_f32_e32 v70, v69, v60
	v_lshlrev_b32_e32 v60, 16, v71
	v_exp_f32_e32 v60, v60
	v_and_b32_e32 v71, 0xffff0000, v71
	s_cmpk_lt_i32 s14, 0x18c0
	s_mov_b32 s56, 0x20000
	v_fma_f32 v69, -v60, v60, 1.0
	v_max_f32_e32 v69, 0, v69
	v_sqrt_f32_e32 v69, v69
	s_mov_b32 s70, 0x800000
	s_mov_b32 s91, 0xe0000
	s_mov_b32 s68, 0x120000
	v_mul_f32_e32 v69, v69, v71
	v_fmac_f32_e32 v69, v60, v61
	v_lshlrev_b32_e32 v60, 16, v68
	v_and_b32_e32 v61, 0xffff0000, v68
	v_mul_f32_e32 v68, 0x3d372713, v60
	v_mul_f32_e32 v68, v68, v60
	v_fma_f32 v68, v68, v60, v60
	v_mul_f32_e32 v68, 0x3fcc422a, v68
	v_mul_f32_e32 v68, 0xbfb8aa3b, v68
	v_exp_f32_e32 v68, v68
	s_mov_b32 s86, 0x200000
	s_mov_b32 s69, 0x220000
	s_mov_b32 s83, 0x460000
	v_add_f32_e32 v68, 1.0, v68
	v_rcp_f32_e32 v68, v68
	s_mov_b32 s90, 0x4c0000
	s_mov_b32 s84, 0x340000
	s_mov_b32 s85, 0x3e0000
	v_mul_f32_e32 v60, v68, v60
	v_add_f32_e32 v68, v163, v70
	v_mul_f32_e32 v60, v68, v60
	v_mul_f32_e32 v68, 0x3d372713, v61
	v_mul_f32_e32 v68, v68, v61
	v_fma_f32 v68, v68, v61, v61
	v_mul_f32_e32 v68, 0x3fcc422a, v68
	v_mul_f32_e32 v68, 0xbfb8aa3b, v68
	v_exp_f32_e32 v68, v68
	s_mov_b32 s94, 0x420000
	v_readlane_b32 s5, v255, 10
	v_add_f32_e32 v68, 1.0, v68
	v_rcp_f32_e32 v68, v68
	s_nop 0
	v_mul_f32_e32 v61, v68, v61
	v_add_f32_e32 v68, v161, v69
	v_mul_f32_e32 v61, v68, v61
	v_bfe_u32 v68, v60, 16, 1
	v_add3_u32 v60, v60, v68, s8
	v_bfe_u32 v68, v61, 16, 1
	v_lshrrev_b32_e32 v60, 16, v60
	v_add3_u32 v61, v61, v68, s8
	v_and_or_b32 v68, v61, s58, v60
	v_add_co_u32_e32 v60, vcc, s3, v12
	s_mov_b32 s3, 0x27000
	s_nop 0
	v_addc_co_u32_e32 v61, vcc, 0, v13, vcc
	global_store_dword v[60:61], v68, off offset:2560
	v_lshlrev_b32_e32 v60, 16, v66
	v_exp_f32_e32 v60, v60
	v_and_b32_e32 v66, 0xffff0000, v66
	v_fma_f32 v61, -v60, v60, 1.0
	v_max_f32_e32 v61, 0, v61
	v_sqrt_f32_e32 v61, v61
	s_nop 0
	v_mul_f32_e32 v66, v61, v66
	v_fmac_f32_e32 v66, v60, v70
	v_lshlrev_b32_e32 v60, 16, v67
	v_exp_f32_e32 v60, v60
	v_and_b32_e32 v67, 0xffff0000, v67
	v_fma_f32 v61, -v60, v60, 1.0
	v_max_f32_e32 v61, 0, v61
	v_sqrt_f32_e32 v61, v61
	s_nop 0
	v_mul_f32_e32 v67, v61, v67
	v_fmac_f32_e32 v67, v60, v69
	v_lshlrev_b32_e32 v60, 16, v167
	v_mul_f32_e32 v68, 0x3d372713, v60
	v_mul_f32_e32 v68, v68, v60
	v_fma_f32 v68, v68, v60, v60
	v_mul_f32_e32 v68, 0x3fcc422a, v68
	v_mul_f32_e32 v68, 0xbfb8aa3b, v68
	v_exp_f32_e32 v68, v68
	v_and_b32_e32 v61, 0xffff0000, v167
	v_add_f32_e32 v68, 1.0, v68
	v_rcp_f32_e32 v68, v68
	s_nop 0
	v_mul_f32_e32 v60, v68, v60
	v_add_f32_e32 v68, v160, v66
	v_mul_f32_e32 v60, v68, v60
	v_mul_f32_e32 v68, 0x3d372713, v61
	v_mul_f32_e32 v68, v68, v61
	v_fma_f32 v68, v68, v61, v61
	v_mul_f32_e32 v68, 0x3fcc422a, v68
	v_mul_f32_e32 v68, 0xbfb8aa3b, v68
	v_exp_f32_e32 v68, v68
	s_nop 0
; __device__ __forceinline__ unsigned pk2(float lo, float hi) { return f2bf(lo) | (f2bf(hi) << 16); }
; __device__ __forceinline__ float fast_sigmoid(float x) { return fast_rcp(1.f + fast_exp2(-1.4426950408889634f * x)); }
; #define LRU_STEP(h, l, x) do { const float a_ = fast_exp2(l); h = fmaf(a_, h, __builtin_amdgcn_sqrtf(fmaxf(fmaf(-a_, a_, 1.f), 0.f)) * (x)); } while (0)
; __global__ void __launch_bounds__(NTHREADS, 2) mega(Args args) {
;     ...
; #pragma unroll
;                       for (int t = 31; t >= 0; --t) { LRU_STEP(h0, bf_lo(lb[t].x), bf_hi(lb[t].x)); LRU_STEP(h1, bf_lo(lb[t].y), bf_hi(lb[t].y));
;                           const float g0 = bf_lo(gwv[t]), g1 = bf_hi(gwv[t]);
;                           const float z0 = g0 * fast_sigmoid(1.5957691216057308f * (g0 + 0.044715f * g0 * g0 * g0)) * (hf0[t] + h0);
;                           const float z1 = g1 * fast_sigmoid(1.5957691216057308f * (g1 + 0.044715f * g1 * g1 * g1)) * (hf1[t] + h1);
;                           *(unsigned*)(Zb + ro + (size_t)t * LW) = pk2(z0, z1); } }
	v_add_f32_e32 v68, 1.0, v68
	v_rcp_f32_e32 v68, v68
	s_nop 0
	v_mul_f32_e32 v61, v68, v61
	v_add_f32_e32 v68, v158, v67
	v_mul_f32_e32 v61, v68, v61
	v_bfe_u32 v68, v60, 16, 1
	v_add3_u32 v60, v60, v68, s8
	v_bfe_u32 v68, v61, 16, 1
	v_lshrrev_b32_e32 v60, 16, v60
	v_add3_u32 v61, v61, v68, s8
	v_and_or_b32 v68, v61, s58, v60
	v_add_co_u32_e32 v60, vcc, s53, v12
	s_nop 1
	v_addc_co_u32_e32 v61, vcc, 0, v13, vcc
	global_store_dword v[60:61], v68, off offset:1024
	v_lshlrev_b32_e32 v60, 16, v64
	v_exp_f32_e32 v60, v60
	v_and_b32_e32 v64, 0xffff0000, v64
	v_fma_f32 v61, -v60, v60, 1.0
	v_max_f32_e32 v61, 0, v61
	v_sqrt_f32_e32 v61, v61
	s_nop 0
	v_mul_f32_e32 v64, v61, v64
	v_fmac_f32_e32 v64, v60, v66
	v_lshlrev_b32_e32 v60, 16, v65
	v_exp_f32_e32 v60, v60
	v_and_b32_e32 v65, 0xffff0000, v65
	v_fma_f32 v61, -v60, v60, 1.0
	v_max_f32_e32 v61, 0, v61
	v_sqrt_f32_e32 v61, v61
	s_nop 0
	v_mul_f32_e32 v65, v61, v65
	v_fmac_f32_e32 v65, v60, v67
	v_lshlrev_b32_e32 v60, 16, v166
	v_mul_f32_e32 v66, 0x3d372713, v60
	v_mul_f32_e32 v66, v66, v60
	v_fma_f32 v66, v66, v60, v60
	v_mul_f32_e32 v66, 0x3fcc422a, v66
	v_mul_f32_e32 v66, 0xbfb8aa3b, v66
	v_exp_f32_e32 v66, v66
	v_and_b32_e32 v61, 0xffff0000, v166
	v_add_f32_e32 v66, 1.0, v66
	v_rcp_f32_e32 v66, v66
	s_nop 0
	v_mul_f32_e32 v60, v66, v60
	v_add_f32_e32 v66, v157, v64
	v_mul_f32_e32 v60, v66, v60
	v_mul_f32_e32 v66, 0x3d372713, v61
	v_mul_f32_e32 v66, v66, v61
	v_fma_f32 v66, v66, v61, v61
	v_mul_f32_e32 v66, 0x3fcc422a, v66
	v_mul_f32_e32 v66, 0xbfb8aa3b, v66
	v_exp_f32_e32 v66, v66
	s_nop 0
	v_add_f32_e32 v66, 1.0, v66
	v_rcp_f32_e32 v66, v66
	s_nop 0
	v_mul_f32_e32 v61, v66, v61
	v_add_f32_e32 v66, v155, v65
	v_mul_f32_e32 v61, v66, v61
	v_bfe_u32 v66, v60, 16, 1
	v_add3_u32 v60, v60, v66, s8
	v_bfe_u32 v66, v61, 16, 1
	v_lshrrev_b32_e32 v60, 16, v60
	v_add3_u32 v61, v61, v66, s8
	v_and_or_b32 v66, v61, s58, v60
	v_add_co_u32_e32 v60, vcc, s3, v12
	s_mov_b32 s3, 0x25000
	s_nop 0
	v_addc_co_u32_e32 v61, vcc, 0, v13, vcc
	global_store_dword v[60:61], v66, off offset:3584
	v_lshlrev_b32_e32 v60, 16, v62
	v_exp_f32_e32 v60, v60
	v_and_b32_e32 v62, 0xffff0000, v62
	v_fma_f32 v61, -v60, v60, 1.0
	v_max_f32_e32 v61, 0, v61
	v_sqrt_f32_e32 v61, v61
	s_nop 0
	v_mul_f32_e32 v62, v61, v62
	v_fmac_f32_e32 v62, v60, v64
	v_lshlrev_b32_e32 v60, 16, v63
	v_exp_f32_e32 v60, v60
	v_and_b32_e32 v63, 0xffff0000, v63
	v_fma_f32 v61, -v60, v60, 1.0
	v_max_f32_e32 v61, 0, v61
	v_sqrt_f32_e32 v61, v61
	s_nop 0
	v_mul_f32_e32 v63, v61, v63
	v_fmac_f32_e32 v63, v60, v65
	v_lshlrev_b32_e32 v60, 16, v165
	v_mul_f32_e32 v64, 0x3d372713, v60
	v_mul_f32_e32 v64, v64, v60
	v_fma_f32 v64, v64, v60, v60
	v_mul_f32_e32 v64, 0x3fcc422a, v64
	v_mul_f32_e32 v64, 0xbfb8aa3b, v64
	v_exp_f32_e32 v64, v64
	v_and_b32_e32 v61, 0xffff0000, v165
	v_add_f32_e32 v64, 1.0, v64
	v_rcp_f32_e32 v64, v64
	s_nop 0
	v_mul_f32_e32 v60, v64, v60
	v_add_f32_e32 v64, v154, v62
	v_mul_f32_e32 v60, v64, v60
	v_mul_f32_e32 v64, 0x3d372713, v61
	v_mul_f32_e32 v64, v64, v61
	v_fma_f32 v64, v64, v61, v61
	v_mul_f32_e32 v64, 0x3fcc422a, v64
	v_mul_f32_e32 v64, 0xbfb8aa3b, v64
	v_exp_f32_e32 v64, v64
	s_nop 0
	v_add_f32_e32 v64, 1.0, v64
	v_rcp_f32_e32 v64, v64
	s_nop 0
	v_mul_f32_e32 v61, v64, v61
	v_add_f32_e32 v64, v152, v63
	v_mul_f32_e32 v61, v64, v61
	v_bfe_u32 v64, v60, 16, 1
	v_add3_u32 v60, v60, v64, s8
	v_bfe_u32 v64, v61, 16, 1
	v_lshrrev_b32_e32 v60, 16, v60
	v_add3_u32 v61, v61, v64, s8
	v_and_or_b32 v64, v61, s58, v60
	v_add_co_u32_e32 v60, vcc, s52, v12
	s_nop 1
	v_addc_co_u32_e32 v61, vcc, 0, v13, vcc
	global_store_dword v[60:61], v64, off offset:2048
	v_lshlrev_b32_e32 v60, 16, v58
	v_exp_f32_e32 v60, v60
	v_and_b32_e32 v58, 0xffff0000, v58
	v_fma_f32 v61, -v60, v60, 1.0
	v_max_f32_e32 v61, 0, v61
	v_sqrt_f32_e32 v61, v61
	s_nop 0
	v_mul_f32_e32 v61, v61, v58
	v_lshlrev_b32_e32 v58, 16, v59
	v_exp_f32_e32 v58, v58
	v_fmac_f32_e32 v61, v60, v62
	v_and_b32_e32 v59, 0xffff0000, v59
	v_fma_f32 v60, -v58, v58, 1.0
	v_max_f32_e32 v60, 0, v60
	v_sqrt_f32_e32 v60, v60
	s_nop 0
	v_mul_f32_e32 v60, v60, v59
	v_fmac_f32_e32 v60, v58, v63
	v_lshlrev_b32_e32 v58, 16, v164
	v_mul_f32_e32 v62, 0x3d372713, v58
	v_mul_f32_e32 v62, v62, v58
	v_fma_f32 v62, v62, v58, v58
	v_mul_f32_e32 v62, 0x3fcc422a, v62
	v_mul_f32_e32 v62, 0xbfb8aa3b, v62
	v_exp_f32_e32 v62, v62
	v_and_b32_e32 v59, 0xffff0000, v164
	v_add_f32_e32 v62, 1.0, v62
	v_rcp_f32_e32 v62, v62
	s_nop 0
	v_mul_f32_e32 v58, v62, v58
	v_add_f32_e32 v62, v151, v61
	v_mul_f32_e32 v58, v62, v58
	v_mul_f32_e32 v62, 0x3d372713, v59
	v_mul_f32_e32 v62, v62, v59
	v_fma_f32 v62, v62, v59, v59
	v_mul_f32_e32 v62, 0x3fcc422a, v62
	v_mul_f32_e32 v62, 0xbfb8aa3b, v62
	v_exp_f32_e32 v62, v62
	s_nop 0
	v_add_f32_e32 v62, 1.0, v62
	v_rcp_f32_e32 v62, v62
	s_nop 0
	v_mul_f32_e32 v59, v62, v59
	v_add_f32_e32 v62, v149, v60
	v_mul_f32_e32 v59, v62, v59
	v_bfe_u32 v62, v58, 16, 1
	v_add3_u32 v58, v58, v62, s8
	v_bfe_u32 v62, v59, 16, 1
	v_lshrrev_b32_e32 v58, 16, v58
	v_add3_u32 v59, v59, v62, s8
	v_and_or_b32 v62, v59, s58, v58
	v_add_co_u32_e32 v58, vcc, s3, v12
	s_mov_b32 s3, 0x22000
	s_nop 0
	v_addc_co_u32_e32 v59, vcc, 0, v13, vcc
	global_store_dword v[58:59], v62, off offset:512
	v_lshlrev_b32_e32 v58, 16, v56
	v_exp_f32_e32 v58, v58
	v_and_b32_e32 v56, 0xffff0000, v56
	v_fma_f32 v59, -v58, v58, 1.0
	v_max_f32_e32 v59, 0, v59
	v_sqrt_f32_e32 v59, v59
	s_nop 0
	v_mul_f32_e32 v59, v59, v56
	v_lshlrev_b32_e32 v56, 16, v57
	v_exp_f32_e32 v56, v56
	v_fmac_f32_e32 v59, v58, v61
	v_and_b32_e32 v57, 0xffff0000, v57
	v_fma_f32 v58, -v56, v56, 1.0
	v_max_f32_e32 v58, 0, v58
	v_sqrt_f32_e32 v58, v58
	s_nop 0
; __device__ __forceinline__ unsigned pk2(float lo, float hi) { return f2bf(lo) | (f2bf(hi) << 16); }
; __device__ __forceinline__ float fast_sigmoid(float x) { return fast_rcp(1.f + fast_exp2(-1.4426950408889634f * x)); }
; #define LRU_STEP(h, l, x) do { const float a_ = fast_exp2(l); h = fmaf(a_, h, __builtin_amdgcn_sqrtf(fmaxf(fmaf(-a_, a_, 1.f), 0.f)) * (x)); } while (0)
; __global__ void __launch_bounds__(NTHREADS, 2) mega(Args args) {
;     ...
; #pragma unroll
;                       for (int t = 31; t >= 0; --t) { LRU_STEP(h0, bf_lo(lb[t].x), bf_hi(lb[t].x)); LRU_STEP(h1, bf_lo(lb[t].y), bf_hi(lb[t].y));
;                           const float g0 = bf_lo(gwv[t]), g1 = bf_hi(gwv[t]);
;                           const float z0 = g0 * fast_sigmoid(1.5957691216057308f * (g0 + 0.044715f * g0 * g0 * g0)) * (hf0[t] + h0);
;                           const float z1 = g1 * fast_sigmoid(1.5957691216057308f * (g1 + 0.044715f * g1 * g1 * g1)) * (hf1[t] + h1);
;                           *(unsigned*)(Zb + ro + (size_t)t * LW) = pk2(z0, z1); } }
	v_mul_f32_e32 v58, v58, v57
	v_fmac_f32_e32 v58, v56, v60
	v_lshlrev_b32_e32 v56, 16, v162
	v_mul_f32_e32 v60, 0x3d372713, v56
	v_mul_f32_e32 v60, v60, v56
	v_fma_f32 v60, v60, v56, v56
	v_mul_f32_e32 v60, 0x3fcc422a, v60
	v_mul_f32_e32 v60, 0xbfb8aa3b, v60
	v_exp_f32_e32 v60, v60
	v_and_b32_e32 v57, 0xffff0000, v162
	v_add_f32_e32 v60, 1.0, v60
	v_rcp_f32_e32 v60, v60
	s_nop 0
	v_mul_f32_e32 v56, v60, v56
	v_add_f32_e32 v60, v147, v59
	v_mul_f32_e32 v56, v60, v56
	v_mul_f32_e32 v60, 0x3d372713, v57
	v_mul_f32_e32 v60, v60, v57
	v_fma_f32 v60, v60, v57, v57
	v_mul_f32_e32 v60, 0x3fcc422a, v60
	v_mul_f32_e32 v60, 0xbfb8aa3b, v60
	v_exp_f32_e32 v60, v60
	s_nop 0
	v_add_f32_e32 v60, 1.0, v60
	v_rcp_f32_e32 v60, v60
	s_nop 0
	v_mul_f32_e32 v57, v60, v57
	v_add_f32_e32 v60, v146, v58
	v_mul_f32_e32 v57, v60, v57
	v_bfe_u32 v60, v56, 16, 1
	v_add3_u32 v56, v56, v60, s8
	v_bfe_u32 v60, v57, 16, 1
	v_lshrrev_b32_e32 v56, 16, v56
	v_add3_u32 v57, v57, v60, s8
	v_and_or_b32 v60, v57, s58, v56
	v_add_co_u32_e32 v56, vcc, s48, v12
	s_nop 1
	v_addc_co_u32_e32 v57, vcc, 0, v13, vcc
	global_store_dword v[56:57], v60, off offset:3072
	v_lshlrev_b32_e32 v56, 16, v54
	v_exp_f32_e32 v56, v56
	v_and_b32_e32 v54, 0xffff0000, v54
	v_fma_f32 v57, -v56, v56, 1.0
	v_max_f32_e32 v57, 0, v57
	v_sqrt_f32_e32 v57, v57
	s_nop 0
	v_mul_f32_e32 v57, v57, v54
	v_lshlrev_b32_e32 v54, 16, v55
	v_exp_f32_e32 v54, v54
	v_fmac_f32_e32 v57, v56, v59
	v_and_b32_e32 v55, 0xffff0000, v55
	v_fma_f32 v56, -v54, v54, 1.0
	v_max_f32_e32 v56, 0, v56
	v_sqrt_f32_e32 v56, v56
	s_nop 0
	v_mul_f32_e32 v56, v56, v55
	v_fmac_f32_e32 v56, v54, v58
	v_lshlrev_b32_e32 v54, 16, v159
	v_mul_f32_e32 v58, 0x3d372713, v54
	v_mul_f32_e32 v58, v58, v54
	v_fma_f32 v58, v58, v54, v54
	v_mul_f32_e32 v58, 0x3fcc422a, v58
	v_mul_f32_e32 v58, 0xbfb8aa3b, v58
	v_exp_f32_e32 v58, v58
	v_and_b32_e32 v55, 0xffff0000, v159
	v_add_f32_e32 v58, 1.0, v58
	v_rcp_f32_e32 v58, v58
	s_nop 0
	v_mul_f32_e32 v54, v58, v54
	v_add_f32_e32 v58, v144, v57
	v_mul_f32_e32 v54, v58, v54
	v_mul_f32_e32 v58, 0x3d372713, v55
	v_mul_f32_e32 v58, v58, v55
	v_fma_f32 v58, v58, v55, v55
	v_mul_f32_e32 v58, 0x3fcc422a, v58
	v_mul_f32_e32 v58, 0xbfb8aa3b, v58
	v_exp_f32_e32 v58, v58
	s_nop 0
	v_add_f32_e32 v58, 1.0, v58
	v_rcp_f32_e32 v58, v58
	s_nop 0
	v_mul_f32_e32 v55, v58, v55
	v_add_f32_e32 v58, v143, v56
	v_mul_f32_e32 v55, v58, v55
	v_bfe_u32 v58, v54, 16, 1
	v_add3_u32 v54, v54, v58, s8
	v_bfe_u32 v58, v55, 16, 1
	v_lshrrev_b32_e32 v54, 16, v54
	v_add3_u32 v55, v55, v58, s8
	v_and_or_b32 v58, v55, s58, v54
	v_add_co_u32_e32 v54, vcc, s3, v12
	s_mov_b32 s3, 0x1f000
	s_nop 0
	v_addc_co_u32_e32 v55, vcc, 0, v13, vcc
	global_store_dword v[54:55], v58, off offset:1536
	v_lshlrev_b32_e32 v54, 16, v52
	v_exp_f32_e32 v54, v54
	v_and_b32_e32 v52, 0xffff0000, v52
	v_fma_f32 v55, -v54, v54, 1.0
	v_max_f32_e32 v55, 0, v55
	v_sqrt_f32_e32 v55, v55
	s_nop 0
	v_mul_f32_e32 v55, v55, v52
	v_lshlrev_b32_e32 v52, 16, v53
	v_exp_f32_e32 v52, v52
	v_fmac_f32_e32 v55, v54, v57
	v_and_b32_e32 v53, 0xffff0000, v53
	v_fma_f32 v54, -v52, v52, 1.0
	v_max_f32_e32 v54, 0, v54
	v_sqrt_f32_e32 v54, v54
	s_nop 0
	v_mul_f32_e32 v54, v54, v53
	v_fmac_f32_e32 v54, v52, v56
	v_lshlrev_b32_e32 v52, 16, v156
	v_mul_f32_e32 v56, 0x3d372713, v52
	v_mul_f32_e32 v56, v56, v52
	v_fma_f32 v56, v56, v52, v52
	v_mul_f32_e32 v56, 0x3fcc422a, v56
	v_mul_f32_e32 v56, 0xbfb8aa3b, v56
	v_exp_f32_e32 v56, v56
	v_and_b32_e32 v53, 0xffff0000, v156
	v_add_f32_e32 v56, 1.0, v56
	v_rcp_f32_e32 v56, v56
	s_nop 0
	v_mul_f32_e32 v52, v56, v52
	v_add_f32_e32 v56, v141, v55
	v_mul_f32_e32 v52, v56, v52
	v_mul_f32_e32 v56, 0x3d372713, v53
	v_mul_f32_e32 v56, v56, v53
	v_fma_f32 v56, v56, v53, v53
	v_mul_f32_e32 v56, 0x3fcc422a, v56
	v_mul_f32_e32 v56, 0xbfb8aa3b, v56
	v_exp_f32_e32 v56, v56
	s_nop 0
	v_add_f32_e32 v56, 1.0, v56
	v_rcp_f32_e32 v56, v56
	s_nop 0
	v_mul_f32_e32 v53, v56, v53
	v_add_f32_e32 v56, v140, v54
	v_mul_f32_e32 v53, v56, v53
	v_bfe_u32 v56, v52, 16, 1
	v_add3_u32 v52, v52, v56, s8
	v_bfe_u32 v56, v53, 16, 1
	v_lshrrev_b32_e32 v52, 16, v52
	v_add3_u32 v53, v53, v56, s8
	v_and_or_b32 v56, v53, s58, v52
	v_add_co_u32_e32 v52, vcc, s35, v12
	s_nop 1
	v_addc_co_u32_e32 v53, vcc, 0, v13, vcc
	global_store_dword v[52:53], v56, off
	v_lshlrev_b32_e32 v52, 16, v50
	v_exp_f32_e32 v52, v52
	v_and_b32_e32 v50, 0xffff0000, v50
	v_fma_f32 v53, -v52, v52, 1.0
	v_max_f32_e32 v53, 0, v53
	v_sqrt_f32_e32 v53, v53
	s_nop 0
	v_mul_f32_e32 v53, v53, v50
	v_lshlrev_b32_e32 v50, 16, v51
	v_exp_f32_e32 v50, v50
	v_fmac_f32_e32 v53, v52, v55
	v_and_b32_e32 v51, 0xffff0000, v51
	v_fma_f32 v52, -v50, v50, 1.0
	v_max_f32_e32 v52, 0, v52
	v_sqrt_f32_e32 v52, v52
	s_nop 0
	v_mul_f32_e32 v52, v52, v51
	v_fmac_f32_e32 v52, v50, v54
	v_lshlrev_b32_e32 v50, 16, v153
	v_mul_f32_e32 v54, 0x3d372713, v50
	v_mul_f32_e32 v54, v54, v50
	v_fma_f32 v54, v54, v50, v50
	v_mul_f32_e32 v54, 0x3fcc422a, v54
	v_mul_f32_e32 v54, 0xbfb8aa3b, v54
	v_exp_f32_e32 v54, v54
	v_and_b32_e32 v51, 0xffff0000, v153
	v_add_f32_e32 v54, 1.0, v54
	v_rcp_f32_e32 v54, v54
	s_nop 0
	v_mul_f32_e32 v50, v54, v50
	v_add_f32_e32 v54, v138, v53
	v_mul_f32_e32 v50, v54, v50
	v_mul_f32_e32 v54, 0x3d372713, v51
	v_mul_f32_e32 v54, v54, v51
	v_fma_f32 v54, v54, v51, v51
	v_mul_f32_e32 v54, 0x3fcc422a, v54
	v_mul_f32_e32 v54, 0xbfb8aa3b, v54
	v_exp_f32_e32 v54, v54
	s_nop 0
	v_add_f32_e32 v54, 1.0, v54
	v_rcp_f32_e32 v54, v54
	s_nop 0
	v_mul_f32_e32 v51, v54, v51
	v_add_f32_e32 v54, v136, v52
	v_mul_f32_e32 v51, v54, v51
	v_bfe_u32 v54, v50, 16, 1
	v_add3_u32 v50, v50, v54, s8
	v_bfe_u32 v54, v51, 16, 1
	v_lshrrev_b32_e32 v50, 16, v50
; __device__ __forceinline__ unsigned pk2(float lo, float hi) { return f2bf(lo) | (f2bf(hi) << 16); }
; __device__ __forceinline__ float fast_sigmoid(float x) { return fast_rcp(1.f + fast_exp2(-1.4426950408889634f * x)); }
; #define LRU_STEP(h, l, x) do { const float a_ = fast_exp2(l); h = fmaf(a_, h, __builtin_amdgcn_sqrtf(fmaxf(fmaf(-a_, a_, 1.f), 0.f)) * (x)); } while (0)
; __global__ void __launch_bounds__(NTHREADS, 2) mega(Args args) {
;     ...
; #pragma unroll
;                       for (int t = 31; t >= 0; --t) { LRU_STEP(h0, bf_lo(lb[t].x), bf_hi(lb[t].x)); LRU_STEP(h1, bf_lo(lb[t].y), bf_hi(lb[t].y));
;                           const float g0 = bf_lo(gwv[t]), g1 = bf_hi(gwv[t]);
;                           const float z0 = g0 * fast_sigmoid(1.5957691216057308f * (g0 + 0.044715f * g0 * g0 * g0)) * (hf0[t] + h0);
;                           const float z1 = g1 * fast_sigmoid(1.5957691216057308f * (g1 + 0.044715f * g1 * g1 * g1)) * (hf1[t] + h1);
;                           *(unsigned*)(Zb + ro + (size_t)t * LW) = pk2(z0, z1); } }
	v_add3_u32 v51, v51, v54, s8
	v_and_or_b32 v54, v51, s58, v50
	v_add_co_u32_e32 v50, vcc, s3, v12
	s_mov_b32 s3, 0x1c000
	s_nop 0
	v_addc_co_u32_e32 v51, vcc, 0, v13, vcc
	global_store_dword v[50:51], v54, off offset:2560
	v_lshlrev_b32_e32 v50, 16, v48
	v_exp_f32_e32 v50, v50
	v_and_b32_e32 v48, 0xffff0000, v48
	v_fma_f32 v51, -v50, v50, 1.0
	v_max_f32_e32 v51, 0, v51
	v_sqrt_f32_e32 v51, v51
	s_nop 0
	v_mul_f32_e32 v51, v51, v48
	v_lshlrev_b32_e32 v48, 16, v49
	v_exp_f32_e32 v48, v48
	v_fmac_f32_e32 v51, v50, v53
	v_and_b32_e32 v49, 0xffff0000, v49
	v_fma_f32 v50, -v48, v48, 1.0
	v_max_f32_e32 v50, 0, v50
	v_sqrt_f32_e32 v50, v50
	s_nop 0
	v_mul_f32_e32 v50, v50, v49
	v_fmac_f32_e32 v50, v48, v52
	v_lshlrev_b32_e32 v48, 16, v150
	v_mul_f32_e32 v52, 0x3d372713, v48
	v_mul_f32_e32 v52, v52, v48
	v_fma_f32 v52, v52, v48, v48
	v_mul_f32_e32 v52, 0x3fcc422a, v52
	v_mul_f32_e32 v52, 0xbfb8aa3b, v52
	v_exp_f32_e32 v52, v52
	v_and_b32_e32 v49, 0xffff0000, v150
	v_add_f32_e32 v52, 1.0, v52
	v_rcp_f32_e32 v52, v52
	s_nop 0
	v_mul_f32_e32 v48, v52, v48
	v_add_f32_e32 v52, v134, v51
	v_mul_f32_e32 v48, v52, v48
	v_mul_f32_e32 v52, 0x3d372713, v49
	v_mul_f32_e32 v52, v52, v49
	v_fma_f32 v52, v52, v49, v49
	v_mul_f32_e32 v52, 0x3fcc422a, v52
	v_mul_f32_e32 v52, 0xbfb8aa3b, v52
	v_exp_f32_e32 v52, v52
	s_nop 0
	v_add_f32_e32 v52, 1.0, v52
	v_rcp_f32_e32 v52, v52
	s_nop 0
	v_mul_f32_e32 v49, v52, v49
	v_add_f32_e32 v52, v133, v50
	v_mul_f32_e32 v49, v52, v49
	v_bfe_u32 v52, v48, 16, 1
	v_add3_u32 v48, v48, v52, s8
	v_bfe_u32 v52, v49, 16, 1
	v_lshrrev_b32_e32 v48, 16, v48
	v_add3_u32 v49, v49, v52, s8
	v_and_or_b32 v52, v49, s58, v48
	v_add_co_u32_e32 v48, vcc, s23, v12
	s_nop 1
	v_addc_co_u32_e32 v49, vcc, 0, v13, vcc
	global_store_dword v[48:49], v52, off offset:1024
	v_lshlrev_b32_e32 v48, 16, v46
	v_exp_f32_e32 v48, v48
	v_and_b32_e32 v46, 0xffff0000, v46
	v_fma_f32 v49, -v48, v48, 1.0
	v_max_f32_e32 v49, 0, v49
	v_sqrt_f32_e32 v49, v49
	s_nop 0
	v_mul_f32_e32 v49, v49, v46
	v_lshlrev_b32_e32 v46, 16, v47
	v_exp_f32_e32 v46, v46
	v_fmac_f32_e32 v49, v48, v51
	v_and_b32_e32 v47, 0xffff0000, v47
	v_fma_f32 v48, -v46, v46, 1.0
	v_max_f32_e32 v48, 0, v48
	v_sqrt_f32_e32 v48, v48
	s_nop 0
	v_mul_f32_e32 v48, v48, v47
	v_fmac_f32_e32 v48, v46, v50
	v_lshlrev_b32_e32 v46, 16, v148
	v_mul_f32_e32 v50, 0x3d372713, v46
	v_mul_f32_e32 v50, v50, v46
	v_fma_f32 v50, v50, v46, v46
	v_mul_f32_e32 v50, 0x3fcc422a, v50
	v_mul_f32_e32 v50, 0xbfb8aa3b, v50
	v_exp_f32_e32 v50, v50
	v_and_b32_e32 v47, 0xffff0000, v148
	v_add_f32_e32 v50, 1.0, v50
	v_rcp_f32_e32 v50, v50
	s_nop 0
	v_mul_f32_e32 v46, v50, v46
	v_add_f32_e32 v50, v131, v49
	v_mul_f32_e32 v46, v50, v46
	v_mul_f32_e32 v50, 0x3d372713, v47
	v_mul_f32_e32 v50, v50, v47
	v_fma_f32 v50, v50, v47, v47
	v_mul_f32_e32 v50, 0x3fcc422a, v50
	v_mul_f32_e32 v50, 0xbfb8aa3b, v50
	v_exp_f32_e32 v50, v50
	s_nop 0
	v_add_f32_e32 v50, 1.0, v50
	v_rcp_f32_e32 v50, v50
	s_nop 0
	v_mul_f32_e32 v47, v50, v47
	v_add_f32_e32 v50, v130, v48
	v_mul_f32_e32 v47, v50, v47
	v_bfe_u32 v50, v46, 16, 1
	v_add3_u32 v46, v46, v50, s8
	v_bfe_u32 v50, v47, 16, 1
	v_lshrrev_b32_e32 v46, 16, v46
	v_add3_u32 v47, v47, v50, s8
	v_and_or_b32 v50, v47, s58, v46
	v_add_co_u32_e32 v46, vcc, s3, v12
	s_mov_b32 s3, 0x1a000
	s_nop 0
	v_addc_co_u32_e32 v47, vcc, 0, v13, vcc
	global_store_dword v[46:47], v50, off offset:3584
	v_lshlrev_b32_e32 v46, 16, v44
	v_exp_f32_e32 v46, v46
	v_and_b32_e32 v44, 0xffff0000, v44
	v_fma_f32 v47, -v46, v46, 1.0
	v_max_f32_e32 v47, 0, v47
	v_sqrt_f32_e32 v47, v47
	s_nop 0
	v_mul_f32_e32 v47, v47, v44
	v_lshlrev_b32_e32 v44, 16, v45
	v_exp_f32_e32 v44, v44
	v_fmac_f32_e32 v47, v46, v49
	v_and_b32_e32 v45, 0xffff0000, v45
	v_fma_f32 v46, -v44, v44, 1.0
	v_max_f32_e32 v46, 0, v46
	v_sqrt_f32_e32 v46, v46
	s_nop 0
	v_mul_f32_e32 v46, v46, v45
	v_fmac_f32_e32 v46, v44, v48
	v_lshlrev_b32_e32 v44, 16, v145
	v_mul_f32_e32 v48, 0x3d372713, v44
	v_mul_f32_e32 v48, v48, v44
	v_fma_f32 v48, v48, v44, v44
	v_mul_f32_e32 v48, 0x3fcc422a, v48
	v_mul_f32_e32 v48, 0xbfb8aa3b, v48
	v_exp_f32_e32 v48, v48
	v_and_b32_e32 v45, 0xffff0000, v145
	v_add_f32_e32 v48, 1.0, v48
	v_rcp_f32_e32 v48, v48
	s_nop 0
	v_mul_f32_e32 v44, v48, v44
	v_add_f32_e32 v48, v128, v47
	v_mul_f32_e32 v44, v48, v44
	v_mul_f32_e32 v48, 0x3d372713, v45
	v_mul_f32_e32 v48, v48, v45
	v_fma_f32 v48, v48, v45, v45
	v_mul_f32_e32 v48, 0x3fcc422a, v48
	v_mul_f32_e32 v48, 0xbfb8aa3b, v48
	v_exp_f32_e32 v48, v48
	s_nop 0
	v_add_f32_e32 v48, 1.0, v48
	v_rcp_f32_e32 v48, v48
	s_nop 0
	v_mul_f32_e32 v45, v48, v45
	v_add_f32_e32 v48, v127, v46
	v_mul_f32_e32 v45, v48, v45
	v_bfe_u32 v48, v44, 16, 1
	v_add3_u32 v44, v44, v48, s8
	v_bfe_u32 v48, v45, 16, 1
	v_lshrrev_b32_e32 v44, 16, v44
	v_add3_u32 v45, v45, v48, s8
	v_and_or_b32 v48, v45, s58, v44
	v_add_co_u32_e32 v44, vcc, s34, v12
	s_nop 1
	v_addc_co_u32_e32 v45, vcc, 0, v13, vcc
	global_store_dword v[44:45], v48, off offset:2048
	v_lshlrev_b32_e32 v44, 16, v42
	v_exp_f32_e32 v44, v44
	v_and_b32_e32 v42, 0xffff0000, v42
	v_fma_f32 v45, -v44, v44, 1.0
	v_max_f32_e32 v45, 0, v45
	v_sqrt_f32_e32 v45, v45
	s_nop 0
	v_mul_f32_e32 v45, v45, v42
	v_lshlrev_b32_e32 v42, 16, v43
	v_exp_f32_e32 v42, v42
	v_fmac_f32_e32 v45, v44, v47
	v_and_b32_e32 v43, 0xffff0000, v43
	v_fma_f32 v44, -v42, v42, 1.0
	v_max_f32_e32 v44, 0, v44
	v_sqrt_f32_e32 v44, v44
	s_nop 0
	v_mul_f32_e32 v44, v44, v43
	v_fmac_f32_e32 v44, v42, v46
	v_lshlrev_b32_e32 v42, 16, v142
	v_mul_f32_e32 v46, 0x3d372713, v42
	v_mul_f32_e32 v46, v46, v42
	v_fma_f32 v46, v46, v42, v42
	v_mul_f32_e32 v46, 0x3fcc422a, v46
	v_mul_f32_e32 v46, 0xbfb8aa3b, v46
	v_exp_f32_e32 v46, v46
; __device__ __forceinline__ unsigned pk2(float lo, float hi) { return f2bf(lo) | (f2bf(hi) << 16); }
; __device__ __forceinline__ float fast_sigmoid(float x) { return fast_rcp(1.f + fast_exp2(-1.4426950408889634f * x)); }
; #define LRU_STEP(h, l, x) do { const float a_ = fast_exp2(l); h = fmaf(a_, h, __builtin_amdgcn_sqrtf(fmaxf(fmaf(-a_, a_, 1.f), 0.f)) * (x)); } while (0)
; __global__ void __launch_bounds__(NTHREADS, 2) mega(Args args) {
;     ...
; #pragma unroll
;                       for (int t = 31; t >= 0; --t) { LRU_STEP(h0, bf_lo(lb[t].x), bf_hi(lb[t].x)); LRU_STEP(h1, bf_lo(lb[t].y), bf_hi(lb[t].y));
;                           const float g0 = bf_lo(gwv[t]), g1 = bf_hi(gwv[t]);
;                           const float z0 = g0 * fast_sigmoid(1.5957691216057308f * (g0 + 0.044715f * g0 * g0 * g0)) * (hf0[t] + h0);
;                           const float z1 = g1 * fast_sigmoid(1.5957691216057308f * (g1 + 0.044715f * g1 * g1 * g1)) * (hf1[t] + h1);
;                           *(unsigned*)(Zb + ro + (size_t)t * LW) = pk2(z0, z1); } }
	v_and_b32_e32 v43, 0xffff0000, v142
	v_add_f32_e32 v46, 1.0, v46
	v_rcp_f32_e32 v46, v46
	s_nop 0
	v_mul_f32_e32 v42, v46, v42
	v_add_f32_e32 v46, v124, v45
	v_mul_f32_e32 v42, v46, v42
	v_mul_f32_e32 v46, 0x3d372713, v43
	v_mul_f32_e32 v46, v46, v43
	v_fma_f32 v46, v46, v43, v43
	v_mul_f32_e32 v46, 0x3fcc422a, v46
	v_mul_f32_e32 v46, 0xbfb8aa3b, v46
	v_exp_f32_e32 v46, v46
	s_nop 0
	v_add_f32_e32 v46, 1.0, v46
	v_rcp_f32_e32 v46, v46
	s_nop 0
	v_mul_f32_e32 v43, v46, v43
	v_add_f32_e32 v46, v123, v44
	v_mul_f32_e32 v43, v46, v43
	v_bfe_u32 v46, v42, 16, 1
	v_add3_u32 v42, v42, v46, s8
	v_bfe_u32 v46, v43, 16, 1
	v_lshrrev_b32_e32 v42, 16, v42
	v_add3_u32 v43, v43, v46, s8
	v_and_or_b32 v46, v43, s58, v42
	v_add_co_u32_e32 v42, vcc, s3, v12
	s_mov_b32 s3, 0x17000
	s_nop 0
	v_addc_co_u32_e32 v43, vcc, 0, v13, vcc
	global_store_dword v[42:43], v46, off offset:512
	v_lshlrev_b32_e32 v42, 16, v40
	v_exp_f32_e32 v42, v42
	v_and_b32_e32 v40, 0xffff0000, v40
	v_fma_f32 v43, -v42, v42, 1.0
	v_max_f32_e32 v43, 0, v43
	v_sqrt_f32_e32 v43, v43
	s_nop 0
	v_mul_f32_e32 v43, v43, v40
	v_lshlrev_b32_e32 v40, 16, v41
	v_exp_f32_e32 v40, v40
	v_fmac_f32_e32 v43, v42, v45
	v_and_b32_e32 v41, 0xffff0000, v41
	v_fma_f32 v42, -v40, v40, 1.0
	v_max_f32_e32 v42, 0, v42
	v_sqrt_f32_e32 v42, v42
	s_nop 0
	v_mul_f32_e32 v42, v42, v41
	v_fmac_f32_e32 v42, v40, v44
	v_lshlrev_b32_e32 v40, 16, v139
	v_mul_f32_e32 v44, 0x3d372713, v40
	v_mul_f32_e32 v44, v44, v40
	v_fma_f32 v44, v44, v40, v40
	v_mul_f32_e32 v44, 0x3fcc422a, v44
	v_mul_f32_e32 v44, 0xbfb8aa3b, v44
	v_exp_f32_e32 v44, v44
	v_and_b32_e32 v41, 0xffff0000, v139
	v_add_f32_e32 v44, 1.0, v44
	v_rcp_f32_e32 v44, v44
	s_nop 0
	v_mul_f32_e32 v40, v44, v40
	v_add_f32_e32 v44, v121, v43
	v_mul_f32_e32 v40, v44, v40
	v_mul_f32_e32 v44, 0x3d372713, v41
	v_mul_f32_e32 v44, v44, v41
	v_fma_f32 v44, v44, v41, v41
	v_mul_f32_e32 v44, 0x3fcc422a, v44
	v_mul_f32_e32 v44, 0xbfb8aa3b, v44
	v_exp_f32_e32 v44, v44
	s_nop 0
	v_add_f32_e32 v44, 1.0, v44
	v_rcp_f32_e32 v44, v44
	s_nop 0
	v_mul_f32_e32 v41, v44, v41
	v_add_f32_e32 v44, v120, v42
	v_mul_f32_e32 v41, v44, v41
	v_bfe_u32 v44, v40, 16, 1
	v_add3_u32 v40, v40, v44, s8
	v_bfe_u32 v44, v41, 16, 1
	v_lshrrev_b32_e32 v40, 16, v40
	v_add3_u32 v41, v41, v44, s8
	v_and_or_b32 v44, v41, s58, v40
	v_add_co_u32_e32 v40, vcc, s33, v12
	s_nop 1
	v_addc_co_u32_e32 v41, vcc, 0, v13, vcc
	global_store_dword v[40:41], v44, off offset:3072
	v_lshlrev_b32_e32 v40, 16, v38
	v_exp_f32_e32 v40, v40
	v_and_b32_e32 v38, 0xffff0000, v38
	v_fma_f32 v41, -v40, v40, 1.0
	v_max_f32_e32 v41, 0, v41
	v_sqrt_f32_e32 v41, v41
	s_nop 0
	v_mul_f32_e32 v41, v41, v38
	v_lshlrev_b32_e32 v38, 16, v39
	v_exp_f32_e32 v38, v38
	v_fmac_f32_e32 v41, v40, v43
	v_and_b32_e32 v39, 0xffff0000, v39
	v_fma_f32 v40, -v38, v38, 1.0
	v_max_f32_e32 v40, 0, v40
	v_sqrt_f32_e32 v40, v40
	s_nop 0
	v_mul_f32_e32 v40, v40, v39
	v_fmac_f32_e32 v40, v38, v42
	v_lshlrev_b32_e32 v38, 16, v137
	v_mul_f32_e32 v42, 0x3d372713, v38
	v_mul_f32_e32 v42, v42, v38
	v_fma_f32 v42, v42, v38, v38
	v_mul_f32_e32 v42, 0x3fcc422a, v42
	v_mul_f32_e32 v42, 0xbfb8aa3b, v42
	v_exp_f32_e32 v42, v42
	v_and_b32_e32 v39, 0xffff0000, v137
	v_add_f32_e32 v42, 1.0, v42
	v_rcp_f32_e32 v42, v42
	s_nop 0
	v_mul_f32_e32 v38, v42, v38
	v_add_f32_e32 v42, v118, v41
	v_mul_f32_e32 v38, v42, v38
	v_mul_f32_e32 v42, 0x3d372713, v39
	v_mul_f32_e32 v42, v42, v39
	v_fma_f32 v42, v42, v39, v39
	v_mul_f32_e32 v42, 0x3fcc422a, v42
	v_mul_f32_e32 v42, 0xbfb8aa3b, v42
	v_exp_f32_e32 v42, v42
	s_nop 0
	v_add_f32_e32 v42, 1.0, v42
	v_rcp_f32_e32 v42, v42
	s_nop 0
	v_mul_f32_e32 v39, v42, v39
	v_add_f32_e32 v42, v117, v40
	v_mul_f32_e32 v39, v42, v39
	v_bfe_u32 v42, v38, 16, 1
	v_add3_u32 v38, v38, v42, s8
	v_bfe_u32 v42, v39, 16, 1
	v_lshrrev_b32_e32 v38, 16, v38
	v_add3_u32 v39, v39, v42, s8
	v_and_or_b32 v42, v39, s58, v38
	v_add_co_u32_e32 v38, vcc, s3, v12
	s_mov_b32 s3, 0x14000
	s_nop 0
	v_addc_co_u32_e32 v39, vcc, 0, v13, vcc
	global_store_dword v[38:39], v42, off offset:1536
	v_lshlrev_b32_e32 v38, 16, v36
	v_exp_f32_e32 v38, v38
	v_and_b32_e32 v36, 0xffff0000, v36
	v_fma_f32 v39, -v38, v38, 1.0
	v_max_f32_e32 v39, 0, v39
	v_sqrt_f32_e32 v39, v39
	s_nop 0
	v_mul_f32_e32 v39, v39, v36
	v_lshlrev_b32_e32 v36, 16, v37
	v_exp_f32_e32 v36, v36
	v_fmac_f32_e32 v39, v38, v41
	v_and_b32_e32 v37, 0xffff0000, v37
	v_fma_f32 v38, -v36, v36, 1.0
	v_max_f32_e32 v38, 0, v38
	v_sqrt_f32_e32 v38, v38
	s_nop 0
	v_mul_f32_e32 v38, v38, v37
	v_fmac_f32_e32 v38, v36, v40
	v_lshlrev_b32_e32 v36, 16, v135
	v_mul_f32_e32 v40, 0x3d372713, v36
	v_mul_f32_e32 v40, v40, v36
	v_fma_f32 v40, v40, v36, v36
	v_mul_f32_e32 v40, 0x3fcc422a, v40
	v_mul_f32_e32 v40, 0xbfb8aa3b, v40
	v_exp_f32_e32 v40, v40
	v_and_b32_e32 v37, 0xffff0000, v135
	v_add_f32_e32 v40, 1.0, v40
	v_rcp_f32_e32 v40, v40
	s_nop 0
	v_mul_f32_e32 v36, v40, v36
	v_add_f32_e32 v40, v115, v39
	v_mul_f32_e32 v36, v40, v36
	v_mul_f32_e32 v40, 0x3d372713, v37
	v_mul_f32_e32 v40, v40, v37
	v_fma_f32 v40, v40, v37, v37
	v_mul_f32_e32 v40, 0x3fcc422a, v40
	v_mul_f32_e32 v40, 0xbfb8aa3b, v40
	v_exp_f32_e32 v40, v40
	s_nop 0
	v_add_f32_e32 v40, 1.0, v40
	v_rcp_f32_e32 v40, v40
	s_nop 0
	v_mul_f32_e32 v37, v40, v37
	v_add_f32_e32 v40, v114, v38
	v_mul_f32_e32 v37, v40, v37
	v_bfe_u32 v40, v36, 16, 1
	v_add3_u32 v36, v36, v40, s8
	v_bfe_u32 v40, v37, 16, 1
	v_lshrrev_b32_e32 v36, 16, v36
	v_add3_u32 v37, v37, v40, s8
	v_and_or_b32 v40, v37, s58, v36
	v_add_co_u32_e32 v36, vcc, s21, v12
	s_nop 1
	v_addc_co_u32_e32 v37, vcc, 0, v13, vcc
	global_store_dword v[36:37], v40, off
	v_lshlrev_b32_e32 v36, 16, v34
	v_exp_f32_e32 v36, v36
; __device__ __forceinline__ unsigned pk2(float lo, float hi) { return f2bf(lo) | (f2bf(hi) << 16); }
; __device__ __forceinline__ float fast_sigmoid(float x) { return fast_rcp(1.f + fast_exp2(-1.4426950408889634f * x)); }
; #define LRU_STEP(h, l, x) do { const float a_ = fast_exp2(l); h = fmaf(a_, h, __builtin_amdgcn_sqrtf(fmaxf(fmaf(-a_, a_, 1.f), 0.f)) * (x)); } while (0)
; __global__ void __launch_bounds__(NTHREADS, 2) mega(Args args) {
;     ...
; #pragma unroll
;                       for (int t = 31; t >= 0; --t) { LRU_STEP(h0, bf_lo(lb[t].x), bf_hi(lb[t].x)); LRU_STEP(h1, bf_lo(lb[t].y), bf_hi(lb[t].y));
;                           const float g0 = bf_lo(gwv[t]), g1 = bf_hi(gwv[t]);
;                           const float z0 = g0 * fast_sigmoid(1.5957691216057308f * (g0 + 0.044715f * g0 * g0 * g0)) * (hf0[t] + h0);
;                           const float z1 = g1 * fast_sigmoid(1.5957691216057308f * (g1 + 0.044715f * g1 * g1 * g1)) * (hf1[t] + h1);
;                           *(unsigned*)(Zb + ro + (size_t)t * LW) = pk2(z0, z1); } }
	v_and_b32_e32 v34, 0xffff0000, v34
	v_fma_f32 v37, -v36, v36, 1.0
	v_max_f32_e32 v37, 0, v37
	v_sqrt_f32_e32 v37, v37
	s_nop 0
	v_mul_f32_e32 v37, v37, v34
	v_lshlrev_b32_e32 v34, 16, v35
	v_exp_f32_e32 v34, v34
	v_fmac_f32_e32 v37, v36, v39
	v_and_b32_e32 v35, 0xffff0000, v35
	v_fma_f32 v36, -v34, v34, 1.0
	v_max_f32_e32 v36, 0, v36
	v_sqrt_f32_e32 v36, v36
	s_nop 0
	v_mul_f32_e32 v36, v36, v35
	v_fmac_f32_e32 v36, v34, v38
	v_lshlrev_b32_e32 v34, 16, v132
	v_mul_f32_e32 v38, 0x3d372713, v34
	v_mul_f32_e32 v38, v38, v34
	v_fma_f32 v38, v38, v34, v34
	v_mul_f32_e32 v38, 0x3fcc422a, v38
	v_mul_f32_e32 v38, 0xbfb8aa3b, v38
	v_exp_f32_e32 v38, v38
	v_and_b32_e32 v35, 0xffff0000, v132
	v_add_f32_e32 v38, 1.0, v38
	v_rcp_f32_e32 v38, v38
	s_nop 0
	v_mul_f32_e32 v34, v38, v34
	v_add_f32_e32 v38, v111, v37
	v_mul_f32_e32 v34, v38, v34
	v_mul_f32_e32 v38, 0x3d372713, v35
	v_mul_f32_e32 v38, v38, v35
	v_fma_f32 v38, v38, v35, v35
	v_mul_f32_e32 v38, 0x3fcc422a, v38
	v_mul_f32_e32 v38, 0xbfb8aa3b, v38
	v_exp_f32_e32 v38, v38
	s_nop 0
	v_add_f32_e32 v38, 1.0, v38
	v_rcp_f32_e32 v38, v38
	s_nop 0
	v_mul_f32_e32 v35, v38, v35
	v_add_f32_e32 v38, v110, v36
	v_mul_f32_e32 v35, v38, v35
	v_bfe_u32 v38, v34, 16, 1
	v_add3_u32 v34, v34, v38, s8
	v_bfe_u32 v38, v35, 16, 1
	v_lshrrev_b32_e32 v34, 16, v34
	v_add3_u32 v35, v35, v38, s8
	v_and_or_b32 v38, v35, s58, v34
	v_add_co_u32_e32 v34, vcc, s3, v12
	s_mov_b32 s3, 0x11000
	s_nop 0
	v_addc_co_u32_e32 v35, vcc, 0, v13, vcc
	global_store_dword v[34:35], v38, off offset:2560
	v_lshlrev_b32_e32 v34, 16, v32
	v_exp_f32_e32 v34, v34
	v_and_b32_e32 v32, 0xffff0000, v32
	v_fma_f32 v35, -v34, v34, 1.0
	v_max_f32_e32 v35, 0, v35
	v_sqrt_f32_e32 v35, v35
	s_nop 0
	v_mul_f32_e32 v35, v35, v32
	v_lshlrev_b32_e32 v32, 16, v33
	v_exp_f32_e32 v32, v32
	v_fmac_f32_e32 v35, v34, v37
	v_and_b32_e32 v33, 0xffff0000, v33
	v_fma_f32 v34, -v32, v32, 1.0
	v_max_f32_e32 v34, 0, v34
	v_sqrt_f32_e32 v34, v34
	s_nop 0
	v_mul_f32_e32 v34, v34, v33
	v_fmac_f32_e32 v34, v32, v36
	v_lshlrev_b32_e32 v32, 16, v129
	v_mul_f32_e32 v36, 0x3d372713, v32
	v_mul_f32_e32 v36, v36, v32
	v_fma_f32 v36, v36, v32, v32
	v_mul_f32_e32 v36, 0x3fcc422a, v36
	v_mul_f32_e32 v36, 0xbfb8aa3b, v36
	v_exp_f32_e32 v36, v36
	v_and_b32_e32 v33, 0xffff0000, v129
	v_add_f32_e32 v36, 1.0, v36
	v_rcp_f32_e32 v36, v36
	s_nop 0
	v_mul_f32_e32 v32, v36, v32
	v_add_f32_e32 v36, v108, v35
	v_mul_f32_e32 v32, v36, v32
	v_mul_f32_e32 v36, 0x3d372713, v33
	v_mul_f32_e32 v36, v36, v33
	v_fma_f32 v36, v36, v33, v33
	v_mul_f32_e32 v36, 0x3fcc422a, v36
	v_mul_f32_e32 v36, 0xbfb8aa3b, v36
	v_exp_f32_e32 v36, v36
	s_nop 0
	v_add_f32_e32 v36, 1.0, v36
	v_rcp_f32_e32 v36, v36
	s_nop 0
	v_mul_f32_e32 v33, v36, v33
	v_add_f32_e32 v36, v107, v34
	v_mul_f32_e32 v33, v36, v33
	v_bfe_u32 v36, v32, 16, 1
	v_add3_u32 v32, v32, v36, s8
	v_bfe_u32 v36, v33, 16, 1
	v_lshrrev_b32_e32 v32, 16, v32
	v_add3_u32 v33, v33, v36, s8
	v_and_or_b32 v36, v33, s58, v32
	v_add_co_u32_e32 v32, vcc, s31, v12
	s_nop 1
	v_addc_co_u32_e32 v33, vcc, 0, v13, vcc
	global_store_dword v[32:33], v36, off offset:1024
	v_lshlrev_b32_e32 v32, 16, v30
	v_exp_f32_e32 v32, v32
	v_and_b32_e32 v30, 0xffff0000, v30
	v_fma_f32 v33, -v32, v32, 1.0
	v_max_f32_e32 v33, 0, v33
	v_sqrt_f32_e32 v33, v33
	s_nop 0
	v_mul_f32_e32 v33, v33, v30
	v_lshlrev_b32_e32 v30, 16, v31
	v_exp_f32_e32 v30, v30
	v_fmac_f32_e32 v33, v32, v35
	v_and_b32_e32 v31, 0xffff0000, v31
	v_fma_f32 v32, -v30, v30, 1.0
	v_max_f32_e32 v32, 0, v32
	v_sqrt_f32_e32 v32, v32
	s_nop 0
	v_mul_f32_e32 v32, v32, v31
	v_fmac_f32_e32 v32, v30, v34
	v_lshlrev_b32_e32 v30, 16, v126
	v_mul_f32_e32 v34, 0x3d372713, v30
	v_mul_f32_e32 v34, v34, v30
	v_fma_f32 v34, v34, v30, v30
	v_mul_f32_e32 v34, 0x3fcc422a, v34
	v_mul_f32_e32 v34, 0xbfb8aa3b, v34
	v_exp_f32_e32 v34, v34
	v_and_b32_e32 v31, 0xffff0000, v126
	v_add_f32_e32 v34, 1.0, v34
	v_rcp_f32_e32 v34, v34
	s_nop 0
	v_mul_f32_e32 v30, v34, v30
	v_add_f32_e32 v34, v105, v33
	v_mul_f32_e32 v30, v34, v30
	v_mul_f32_e32 v34, 0x3d372713, v31
	v_mul_f32_e32 v34, v34, v31
	v_fma_f32 v34, v34, v31, v31
	v_mul_f32_e32 v34, 0x3fcc422a, v34
	v_mul_f32_e32 v34, 0xbfb8aa3b, v34
	v_exp_f32_e32 v34, v34
	s_nop 0
	v_add_f32_e32 v34, 1.0, v34
	v_rcp_f32_e32 v34, v34
	s_nop 0
	v_mul_f32_e32 v31, v34, v31
	v_add_f32_e32 v34, v104, v32
	v_mul_f32_e32 v31, v34, v31
	v_bfe_u32 v34, v30, 16, 1
	v_add3_u32 v30, v30, v34, s8
	v_bfe_u32 v34, v31, 16, 1
	v_lshrrev_b32_e32 v30, 16, v30
	v_add3_u32 v31, v31, v34, s8
	v_and_or_b32 v34, v31, s58, v30
	v_add_co_u32_e32 v30, vcc, s3, v12
	s_mov_b32 s3, 0xf000
	s_nop 0
	v_addc_co_u32_e32 v31, vcc, 0, v13, vcc
	global_store_dword v[30:31], v34, off offset:3584
	v_lshlrev_b32_e32 v30, 16, v28
	v_exp_f32_e32 v30, v30
	v_and_b32_e32 v28, 0xffff0000, v28
	v_fma_f32 v31, -v30, v30, 1.0
	v_max_f32_e32 v31, 0, v31
	v_sqrt_f32_e32 v31, v31
	s_nop 0
	v_mul_f32_e32 v31, v31, v28
	v_lshlrev_b32_e32 v28, 16, v29
	v_exp_f32_e32 v28, v28
	v_fmac_f32_e32 v31, v30, v33
	v_and_b32_e32 v29, 0xffff0000, v29
	v_fma_f32 v30, -v28, v28, 1.0
	v_max_f32_e32 v30, 0, v30
	v_sqrt_f32_e32 v30, v30
	s_nop 0
	v_mul_f32_e32 v30, v30, v29
	v_fmac_f32_e32 v30, v28, v32
	v_lshlrev_b32_e32 v28, 16, v125
	v_mul_f32_e32 v32, 0x3d372713, v28
	v_mul_f32_e32 v32, v32, v28
	v_fma_f32 v32, v32, v28, v28
	v_mul_f32_e32 v32, 0x3fcc422a, v32
	v_mul_f32_e32 v32, 0xbfb8aa3b, v32
	v_exp_f32_e32 v32, v32
	v_and_b32_e32 v29, 0xffff0000, v125
	v_add_f32_e32 v32, 1.0, v32
	v_rcp_f32_e32 v32, v32
	s_nop 0
	v_mul_f32_e32 v28, v32, v28
	v_add_f32_e32 v32, v102, v31
	v_mul_f32_e32 v28, v32, v28
	v_mul_f32_e32 v32, 0x3d372713, v29
	v_mul_f32_e32 v32, v32, v29
; __device__ __forceinline__ unsigned pk2(float lo, float hi) { return f2bf(lo) | (f2bf(hi) << 16); }
; __device__ __forceinline__ float fast_sigmoid(float x) { return fast_rcp(1.f + fast_exp2(-1.4426950408889634f * x)); }
; #define LRU_STEP(h, l, x) do { const float a_ = fast_exp2(l); h = fmaf(a_, h, __builtin_amdgcn_sqrtf(fmaxf(fmaf(-a_, a_, 1.f), 0.f)) * (x)); } while (0)
; __global__ void __launch_bounds__(NTHREADS, 2) mega(Args args) {
;     ...
; #pragma unroll
;                       for (int t = 31; t >= 0; --t) { LRU_STEP(h0, bf_lo(lb[t].x), bf_hi(lb[t].x)); LRU_STEP(h1, bf_lo(lb[t].y), bf_hi(lb[t].y));
;                           const float g0 = bf_lo(gwv[t]), g1 = bf_hi(gwv[t]);
;                           const float z0 = g0 * fast_sigmoid(1.5957691216057308f * (g0 + 0.044715f * g0 * g0 * g0)) * (hf0[t] + h0);
;                           const float z1 = g1 * fast_sigmoid(1.5957691216057308f * (g1 + 0.044715f * g1 * g1 * g1)) * (hf1[t] + h1);
;                           *(unsigned*)(Zb + ro + (size_t)t * LW) = pk2(z0, z1); } }
	v_fma_f32 v32, v32, v29, v29
	v_mul_f32_e32 v32, 0x3fcc422a, v32
	v_mul_f32_e32 v32, 0xbfb8aa3b, v32
	v_exp_f32_e32 v32, v32
	s_nop 0
	v_add_f32_e32 v32, 1.0, v32
	v_rcp_f32_e32 v32, v32
	s_nop 0
	v_mul_f32_e32 v29, v32, v29
	v_add_f32_e32 v32, v100, v30
	v_mul_f32_e32 v29, v32, v29
	v_bfe_u32 v32, v28, 16, 1
	v_add3_u32 v28, v28, v32, s8
	v_bfe_u32 v32, v29, 16, 1
	v_lshrrev_b32_e32 v28, 16, v28
	v_add3_u32 v29, v29, v32, s8
	v_and_or_b32 v32, v29, s58, v28
	v_add_co_u32_e32 v28, vcc, s16, v12
	s_nop 1
	v_addc_co_u32_e32 v29, vcc, 0, v13, vcc
	global_store_dword v[28:29], v32, off offset:2048
	v_lshlrev_b32_e32 v28, 16, v26
	v_exp_f32_e32 v28, v28
	v_and_b32_e32 v26, 0xffff0000, v26
	v_fma_f32 v29, -v28, v28, 1.0
	v_max_f32_e32 v29, 0, v29
	v_sqrt_f32_e32 v29, v29
	s_nop 0
	v_mul_f32_e32 v29, v29, v26
	v_lshlrev_b32_e32 v26, 16, v27
	v_exp_f32_e32 v26, v26
	v_fmac_f32_e32 v29, v28, v31
	v_and_b32_e32 v27, 0xffff0000, v27
	v_fma_f32 v28, -v26, v26, 1.0
	v_max_f32_e32 v28, 0, v28
	v_sqrt_f32_e32 v28, v28
	s_nop 0
	v_mul_f32_e32 v28, v28, v27
	v_fmac_f32_e32 v28, v26, v30
	v_lshlrev_b32_e32 v26, 16, v122
	v_mul_f32_e32 v30, 0x3d372713, v26
	v_mul_f32_e32 v30, v30, v26
	v_fma_f32 v30, v30, v26, v26
	v_mul_f32_e32 v30, 0x3fcc422a, v30
	v_mul_f32_e32 v30, 0xbfb8aa3b, v30
	v_exp_f32_e32 v30, v30
	v_and_b32_e32 v27, 0xffff0000, v122
	v_add_f32_e32 v30, 1.0, v30
	v_rcp_f32_e32 v30, v30
	s_nop 0
	v_mul_f32_e32 v26, v30, v26
	v_add_f32_e32 v30, v98, v29
	v_mul_f32_e32 v26, v30, v26
	v_mul_f32_e32 v30, 0x3d372713, v27
	v_mul_f32_e32 v30, v30, v27
	v_fma_f32 v30, v30, v27, v27
	v_mul_f32_e32 v30, 0x3fcc422a, v30
	v_mul_f32_e32 v30, 0xbfb8aa3b, v30
	v_exp_f32_e32 v30, v30
	s_nop 0
	v_add_f32_e32 v30, 1.0, v30
	v_rcp_f32_e32 v30, v30
	s_nop 0
	v_mul_f32_e32 v27, v30, v27
	v_add_f32_e32 v30, v97, v28
	v_mul_f32_e32 v27, v30, v27
	v_bfe_u32 v30, v26, 16, 1
	v_add3_u32 v26, v26, v30, s8
	v_bfe_u32 v30, v27, 16, 1
	v_lshrrev_b32_e32 v26, 16, v26
	v_add3_u32 v27, v27, v30, s8
	v_and_or_b32 v30, v27, s58, v26
	v_add_co_u32_e32 v26, vcc, s3, v12
	s_mov_b32 s3, 0xc000
	s_nop 0
	v_addc_co_u32_e32 v27, vcc, 0, v13, vcc
	global_store_dword v[26:27], v30, off offset:512
	v_lshlrev_b32_e32 v26, 16, v24
	v_exp_f32_e32 v26, v26
	v_and_b32_e32 v24, 0xffff0000, v24
	v_fma_f32 v27, -v26, v26, 1.0
	v_max_f32_e32 v27, 0, v27
	v_sqrt_f32_e32 v27, v27
	s_nop 0
	v_mul_f32_e32 v27, v27, v24
	v_lshlrev_b32_e32 v24, 16, v25
	v_exp_f32_e32 v24, v24
	v_fmac_f32_e32 v27, v26, v29
	v_and_b32_e32 v25, 0xffff0000, v25
	v_fma_f32 v26, -v24, v24, 1.0
	v_max_f32_e32 v26, 0, v26
	v_sqrt_f32_e32 v26, v26
	s_nop 0
	v_mul_f32_e32 v26, v26, v25
	v_fmac_f32_e32 v26, v24, v28
	v_lshlrev_b32_e32 v24, 16, v119
	v_mul_f32_e32 v28, 0x3d372713, v24
	v_mul_f32_e32 v28, v28, v24
	v_fma_f32 v28, v28, v24, v24
	v_mul_f32_e32 v28, 0x3fcc422a, v28
	v_mul_f32_e32 v28, 0xbfb8aa3b, v28
	v_exp_f32_e32 v28, v28
	v_and_b32_e32 v25, 0xffff0000, v119
	v_add_f32_e32 v28, 1.0, v28
	v_rcp_f32_e32 v28, v28
	s_nop 0
	v_mul_f32_e32 v24, v28, v24
	v_add_f32_e32 v28, v95, v27
	v_mul_f32_e32 v24, v28, v24
	v_mul_f32_e32 v28, 0x3d372713, v25
	v_mul_f32_e32 v28, v28, v25
	v_fma_f32 v28, v28, v25, v25
	v_mul_f32_e32 v28, 0x3fcc422a, v28
	v_mul_f32_e32 v28, 0xbfb8aa3b, v28
	v_exp_f32_e32 v28, v28
	s_nop 0
	v_add_f32_e32 v28, 1.0, v28
	v_rcp_f32_e32 v28, v28
	s_nop 0
	v_mul_f32_e32 v25, v28, v25
	v_add_f32_e32 v28, v94, v26
	v_mul_f32_e32 v25, v28, v25
	v_bfe_u32 v28, v24, 16, 1
	v_add3_u32 v24, v24, v28, s8
	v_bfe_u32 v28, v25, 16, 1
	v_lshrrev_b32_e32 v24, 16, v24
	v_add3_u32 v25, v25, v28, s8
	v_and_or_b32 v28, v25, s58, v24
	v_add_co_u32_e32 v24, vcc, s30, v12
	s_nop 1
	v_addc_co_u32_e32 v25, vcc, 0, v13, vcc
	global_store_dword v[24:25], v28, off offset:3072
	v_lshlrev_b32_e32 v24, 16, v22
	v_exp_f32_e32 v24, v24
	v_and_b32_e32 v22, 0xffff0000, v22
	v_fma_f32 v25, -v24, v24, 1.0
	v_max_f32_e32 v25, 0, v25
	v_sqrt_f32_e32 v25, v25
	s_nop 0
	v_mul_f32_e32 v25, v25, v22
	v_lshlrev_b32_e32 v22, 16, v23
	v_exp_f32_e32 v22, v22
	v_fmac_f32_e32 v25, v24, v27
	v_and_b32_e32 v23, 0xffff0000, v23
	v_fma_f32 v24, -v22, v22, 1.0
	v_max_f32_e32 v24, 0, v24
	v_sqrt_f32_e32 v24, v24
	s_nop 0
	v_mul_f32_e32 v24, v24, v23
	v_fmac_f32_e32 v24, v22, v26
	v_lshlrev_b32_e32 v22, 16, v116
	v_mul_f32_e32 v26, 0x3d372713, v22
	v_mul_f32_e32 v26, v26, v22
	v_fma_f32 v26, v26, v22, v22
	v_mul_f32_e32 v26, 0x3fcc422a, v26
	v_mul_f32_e32 v26, 0xbfb8aa3b, v26
	v_exp_f32_e32 v26, v26
	v_and_b32_e32 v23, 0xffff0000, v116
	v_add_f32_e32 v26, 1.0, v26
	v_rcp_f32_e32 v26, v26
	s_nop 0
	v_mul_f32_e32 v22, v26, v22
	v_add_f32_e32 v26, v92, v25
	v_mul_f32_e32 v22, v26, v22
	v_mul_f32_e32 v26, 0x3d372713, v23
	v_mul_f32_e32 v26, v26, v23
	v_fma_f32 v26, v26, v23, v23
	v_mul_f32_e32 v26, 0x3fcc422a, v26
	v_mul_f32_e32 v26, 0xbfb8aa3b, v26
	v_exp_f32_e32 v26, v26
	s_nop 0
	v_add_f32_e32 v26, 1.0, v26
	v_rcp_f32_e32 v26, v26
	s_nop 0
	v_mul_f32_e32 v23, v26, v23
	v_add_f32_e32 v26, v91, v24
	v_mul_f32_e32 v23, v26, v23
	v_bfe_u32 v26, v22, 16, 1
	v_add3_u32 v22, v22, v26, s8
	v_bfe_u32 v26, v23, 16, 1
	v_lshrrev_b32_e32 v22, 16, v22
	v_add3_u32 v23, v23, v26, s8
	v_and_or_b32 v26, v23, s58, v22
	v_add_co_u32_e32 v22, vcc, s3, v12
	s_mov_b32 s3, 0x9000
	s_nop 0
	v_addc_co_u32_e32 v23, vcc, 0, v13, vcc
	global_store_dword v[22:23], v26, off offset:1536
	v_lshlrev_b32_e32 v22, 16, v20
	v_exp_f32_e32 v22, v22
	v_and_b32_e32 v20, 0xffff0000, v20
	v_fma_f32 v23, -v22, v22, 1.0
	v_max_f32_e32 v23, 0, v23
	v_sqrt_f32_e32 v23, v23
	s_nop 0
	v_mul_f32_e32 v23, v23, v20
	v_lshlrev_b32_e32 v20, 16, v21
	v_exp_f32_e32 v20, v20
	v_fmac_f32_e32 v23, v22, v25
; __device__ __forceinline__ unsigned pk2(float lo, float hi) { return f2bf(lo) | (f2bf(hi) << 16); }
; __device__ __forceinline__ float fast_sigmoid(float x) { return fast_rcp(1.f + fast_exp2(-1.4426950408889634f * x)); }
; #define LRU_STEP(h, l, x) do { const float a_ = fast_exp2(l); h = fmaf(a_, h, __builtin_amdgcn_sqrtf(fmaxf(fmaf(-a_, a_, 1.f), 0.f)) * (x)); } while (0)
; __global__ void __launch_bounds__(NTHREADS, 2) mega(Args args) {
;     ...
; #pragma unroll
;                       for (int t = 31; t >= 0; --t) { LRU_STEP(h0, bf_lo(lb[t].x), bf_hi(lb[t].x)); LRU_STEP(h1, bf_lo(lb[t].y), bf_hi(lb[t].y));
;                           const float g0 = bf_lo(gwv[t]), g1 = bf_hi(gwv[t]);
;                           const float z0 = g0 * fast_sigmoid(1.5957691216057308f * (g0 + 0.044715f * g0 * g0 * g0)) * (hf0[t] + h0);
;                           const float z1 = g1 * fast_sigmoid(1.5957691216057308f * (g1 + 0.044715f * g1 * g1 * g1)) * (hf1[t] + h1);
;                           *(unsigned*)(Zb + ro + (size_t)t * LW) = pk2(z0, z1); } }
	v_and_b32_e32 v21, 0xffff0000, v21
	v_fma_f32 v22, -v20, v20, 1.0
	v_max_f32_e32 v22, 0, v22
	v_sqrt_f32_e32 v22, v22
	s_nop 0
	v_mul_f32_e32 v22, v22, v21
	v_fmac_f32_e32 v22, v20, v24
	v_lshlrev_b32_e32 v20, 16, v113
	v_mul_f32_e32 v24, 0x3d372713, v20
	v_mul_f32_e32 v24, v24, v20
	v_fma_f32 v24, v24, v20, v20
	v_mul_f32_e32 v24, 0x3fcc422a, v24
	v_mul_f32_e32 v24, 0xbfb8aa3b, v24
	v_exp_f32_e32 v24, v24
	v_and_b32_e32 v21, 0xffff0000, v113
	v_add_f32_e32 v24, 1.0, v24
	v_rcp_f32_e32 v24, v24
	s_nop 0
	v_mul_f32_e32 v20, v24, v20
	v_add_f32_e32 v24, v90, v23
	v_mul_f32_e32 v20, v24, v20
	v_mul_f32_e32 v24, 0x3d372713, v21
	v_mul_f32_e32 v24, v24, v21
	v_fma_f32 v24, v24, v21, v21
	v_mul_f32_e32 v24, 0x3fcc422a, v24
	v_mul_f32_e32 v24, 0xbfb8aa3b, v24
	v_exp_f32_e32 v24, v24
	s_nop 0
	v_add_f32_e32 v24, 1.0, v24
	v_rcp_f32_e32 v24, v24
	s_nop 0
	v_mul_f32_e32 v21, v24, v21
	v_add_f32_e32 v24, v89, v22
	v_mul_f32_e32 v21, v24, v21
	v_bfe_u32 v24, v20, 16, 1
	v_add3_u32 v20, v20, v24, s8
	v_bfe_u32 v24, v21, 16, 1
	v_lshrrev_b32_e32 v20, 16, v20
	v_add3_u32 v21, v21, v24, s8
	v_and_or_b32 v24, v21, s58, v20
	v_add_co_u32_e32 v20, vcc, s24, v12
	s_nop 1
	v_addc_co_u32_e32 v21, vcc, 0, v13, vcc
	global_store_dword v[20:21], v24, off
	v_lshlrev_b32_e32 v20, 16, v18
	v_exp_f32_e32 v20, v20
	v_and_b32_e32 v18, 0xffff0000, v18
	v_fma_f32 v21, -v20, v20, 1.0
	v_max_f32_e32 v21, 0, v21
	v_sqrt_f32_e32 v21, v21
	s_nop 0
	v_mul_f32_e32 v21, v21, v18
	v_lshlrev_b32_e32 v18, 16, v19
	v_exp_f32_e32 v18, v18
	v_fmac_f32_e32 v21, v20, v23
	v_and_b32_e32 v19, 0xffff0000, v19
	v_fma_f32 v20, -v18, v18, 1.0
	v_max_f32_e32 v20, 0, v20
	v_sqrt_f32_e32 v20, v20
	s_nop 0
	v_mul_f32_e32 v20, v20, v19
	v_fmac_f32_e32 v20, v18, v22
	v_lshlrev_b32_e32 v18, 16, v112
	v_mul_f32_e32 v22, 0x3d372713, v18
	v_mul_f32_e32 v22, v22, v18
	v_fma_f32 v22, v22, v18, v18
	v_mul_f32_e32 v22, 0x3fcc422a, v22
	v_mul_f32_e32 v22, 0xbfb8aa3b, v22
	v_exp_f32_e32 v22, v22
	v_and_b32_e32 v19, 0xffff0000, v112
	v_add_f32_e32 v22, 1.0, v22
	v_rcp_f32_e32 v22, v22
	s_nop 0
	v_mul_f32_e32 v18, v22, v18
	v_add_f32_e32 v22, v88, v21
	v_mul_f32_e32 v18, v22, v18
	v_mul_f32_e32 v22, 0x3d372713, v19
	v_mul_f32_e32 v22, v22, v19
	v_fma_f32 v22, v22, v19, v19
	v_mul_f32_e32 v22, 0x3fcc422a, v22
	v_mul_f32_e32 v22, 0xbfb8aa3b, v22
	v_exp_f32_e32 v22, v22
	s_nop 0
	v_add_f32_e32 v22, 1.0, v22
	v_rcp_f32_e32 v22, v22
	s_nop 0
	v_mul_f32_e32 v19, v22, v19
	v_add_f32_e32 v22, v87, v20
	v_mul_f32_e32 v19, v22, v19
	v_bfe_u32 v22, v18, 16, 1
	v_add3_u32 v18, v18, v22, s8
	v_bfe_u32 v22, v19, 16, 1
	v_lshrrev_b32_e32 v18, 16, v18
	v_add3_u32 v19, v19, v22, s8
	v_and_or_b32 v22, v19, s58, v18
	v_add_co_u32_e32 v18, vcc, s3, v12
	s_movk_i32 s3, 0x6000
	s_nop 0
	v_addc_co_u32_e32 v19, vcc, 0, v13, vcc
	global_store_dword v[18:19], v22, off offset:2560
	v_lshlrev_b32_e32 v18, 16, v16
	v_exp_f32_e32 v18, v18
	v_and_b32_e32 v16, 0xffff0000, v16
	v_fma_f32 v19, -v18, v18, 1.0
	v_max_f32_e32 v19, 0, v19
	v_sqrt_f32_e32 v19, v19
	s_nop 0
	v_mul_f32_e32 v19, v19, v16
	v_lshlrev_b32_e32 v16, 16, v17
	v_exp_f32_e32 v16, v16
	v_fmac_f32_e32 v19, v18, v21
	v_and_b32_e32 v17, 0xffff0000, v17
	v_fma_f32 v18, -v16, v16, 1.0
	v_max_f32_e32 v18, 0, v18
	v_sqrt_f32_e32 v18, v18
	s_nop 0
	v_mul_f32_e32 v18, v18, v17
	v_fmac_f32_e32 v18, v16, v20
	v_lshlrev_b32_e32 v16, 16, v109
	v_mul_f32_e32 v20, 0x3d372713, v16
	v_mul_f32_e32 v20, v20, v16
	v_fma_f32 v20, v20, v16, v16
	v_mul_f32_e32 v20, 0x3fcc422a, v20
	v_mul_f32_e32 v20, 0xbfb8aa3b, v20
	v_exp_f32_e32 v20, v20
	v_and_b32_e32 v17, 0xffff0000, v109
	v_add_f32_e32 v20, 1.0, v20
	v_rcp_f32_e32 v20, v20
	s_nop 0
	v_mul_f32_e32 v16, v20, v16
	v_add_f32_e32 v20, v86, v19
	v_mul_f32_e32 v16, v20, v16
	v_mul_f32_e32 v20, 0x3d372713, v17
	v_mul_f32_e32 v20, v20, v17
	v_fma_f32 v20, v20, v17, v17
	v_mul_f32_e32 v20, 0x3fcc422a, v20
	v_mul_f32_e32 v20, 0xbfb8aa3b, v20
	v_exp_f32_e32 v20, v20
	s_nop 0
	v_add_f32_e32 v20, 1.0, v20
	v_rcp_f32_e32 v20, v20
	s_nop 0
	v_mul_f32_e32 v17, v20, v17
	v_add_f32_e32 v20, v85, v18
	v_mul_f32_e32 v17, v20, v17
	v_bfe_u32 v20, v16, 16, 1
	v_add3_u32 v16, v16, v20, s8
	v_bfe_u32 v20, v17, 16, 1
	v_lshrrev_b32_e32 v16, 16, v16
	v_add3_u32 v17, v17, v20, s8
	v_and_or_b32 v20, v17, s58, v16
	v_add_co_u32_e32 v16, vcc, s22, v12
	s_nop 1
	v_addc_co_u32_e32 v17, vcc, 0, v13, vcc
	global_store_dword v[16:17], v20, off offset:1024
	v_lshlrev_b32_e32 v16, 16, v14
	v_exp_f32_e32 v16, v16
	v_and_b32_e32 v14, 0xffff0000, v14
	v_fma_f32 v17, -v16, v16, 1.0
	v_max_f32_e32 v17, 0, v17
	v_sqrt_f32_e32 v17, v17
	s_nop 0
	v_mul_f32_e32 v17, v17, v14
	v_lshlrev_b32_e32 v14, 16, v15
	v_exp_f32_e32 v14, v14
	v_fmac_f32_e32 v17, v16, v19
	v_and_b32_e32 v15, 0xffff0000, v15
	v_fma_f32 v16, -v14, v14, 1.0
	v_max_f32_e32 v16, 0, v16
	v_sqrt_f32_e32 v16, v16
	s_nop 0
	v_mul_f32_e32 v16, v16, v15
	v_fmac_f32_e32 v16, v14, v18
	v_lshlrev_b32_e32 v14, 16, v106
	v_mul_f32_e32 v18, 0x3d372713, v14
	v_mul_f32_e32 v18, v18, v14
	v_fma_f32 v18, v18, v14, v14
	v_mul_f32_e32 v18, 0x3fcc422a, v18
	v_mul_f32_e32 v18, 0xbfb8aa3b, v18
	v_exp_f32_e32 v18, v18
	v_and_b32_e32 v15, 0xffff0000, v106
	v_add_f32_e32 v18, 1.0, v18
	v_rcp_f32_e32 v18, v18
	s_nop 0
	v_mul_f32_e32 v14, v18, v14
	v_add_f32_e32 v18, v84, v17
	v_mul_f32_e32 v14, v18, v14
	v_mul_f32_e32 v18, 0x3d372713, v15
	v_mul_f32_e32 v18, v18, v15
	v_fma_f32 v18, v18, v15, v15
	v_mul_f32_e32 v18, 0x3fcc422a, v18
	v_mul_f32_e32 v18, 0xbfb8aa3b, v18
	v_exp_f32_e32 v18, v18
	s_nop 0
	v_add_f32_e32 v18, 1.0, v18
	v_rcp_f32_e32 v18, v18
	s_nop 0
	v_mul_f32_e32 v15, v18, v15
	v_add_f32_e32 v18, v83, v16
	v_mul_f32_e32 v15, v18, v15
; __device__ __forceinline__ unsigned pk2(float lo, float hi) { return f2bf(lo) | (f2bf(hi) << 16); }
; __device__ __forceinline__ float fast_sigmoid(float x) { return fast_rcp(1.f + fast_exp2(-1.4426950408889634f * x)); }
; #define LRU_STEP(h, l, x) do { const float a_ = fast_exp2(l); h = fmaf(a_, h, __builtin_amdgcn_sqrtf(fmaxf(fmaf(-a_, a_, 1.f), 0.f)) * (x)); } while (0)
; __global__ void __launch_bounds__(NTHREADS, 2) mega(Args args) {
;     ...
; #pragma unroll
;                       for (int t = 31; t >= 0; --t) { LRU_STEP(h0, bf_lo(lb[t].x), bf_hi(lb[t].x)); LRU_STEP(h1, bf_lo(lb[t].y), bf_hi(lb[t].y));
;                           const float g0 = bf_lo(gwv[t]), g1 = bf_hi(gwv[t]);
;                           const float z0 = g0 * fast_sigmoid(1.5957691216057308f * (g0 + 0.044715f * g0 * g0 * g0)) * (hf0[t] + h0);
;                           const float z1 = g1 * fast_sigmoid(1.5957691216057308f * (g1 + 0.044715f * g1 * g1 * g1)) * (hf1[t] + h1);
;                           *(unsigned*)(Zb + ro + (size_t)t * LW) = pk2(z0, z1); } }
	v_bfe_u32 v18, v14, 16, 1
	v_add3_u32 v14, v14, v18, s8
	v_bfe_u32 v18, v15, 16, 1
	v_lshrrev_b32_e32 v14, 16, v14
	v_add3_u32 v15, v15, v18, s8
	v_and_or_b32 v18, v15, s58, v14
	v_add_co_u32_e32 v14, vcc, s3, v12
	s_movk_i32 s3, 0x4000
	s_nop 0
	v_addc_co_u32_e32 v15, vcc, 0, v13, vcc
	global_store_dword v[14:15], v18, off offset:3584
	v_lshlrev_b32_e32 v14, 16, v10
	v_exp_f32_e32 v14, v14
	v_and_b32_e32 v10, 0xffff0000, v10
	v_fma_f32 v15, -v14, v14, 1.0
	v_max_f32_e32 v15, 0, v15
	v_sqrt_f32_e32 v15, v15
	s_nop 0
	v_mul_f32_e32 v15, v15, v10
	v_lshlrev_b32_e32 v10, 16, v11
	v_exp_f32_e32 v10, v10
	v_fmac_f32_e32 v15, v14, v17
	v_and_b32_e32 v11, 0xffff0000, v11
	v_fma_f32 v14, -v10, v10, 1.0
	v_max_f32_e32 v14, 0, v14
	v_sqrt_f32_e32 v14, v14
	s_nop 0
	v_mul_f32_e32 v14, v14, v11
	v_fmac_f32_e32 v14, v10, v16
	v_lshlrev_b32_e32 v10, 16, v103
	v_mul_f32_e32 v16, 0x3d372713, v10
	v_mul_f32_e32 v16, v16, v10
	v_fma_f32 v16, v16, v10, v10
	v_mul_f32_e32 v16, 0x3fcc422a, v16
	v_mul_f32_e32 v16, 0xbfb8aa3b, v16
	v_exp_f32_e32 v16, v16
	v_and_b32_e32 v11, 0xffff0000, v103
	v_add_f32_e32 v16, 1.0, v16
	v_rcp_f32_e32 v16, v16
	s_nop 0
	v_mul_f32_e32 v10, v16, v10
	v_add_f32_e32 v16, v82, v15
	v_mul_f32_e32 v10, v16, v10
	v_mul_f32_e32 v16, 0x3d372713, v11
	v_mul_f32_e32 v16, v16, v11
	v_fma_f32 v16, v16, v11, v11
	v_mul_f32_e32 v16, 0x3fcc422a, v16
	v_mul_f32_e32 v16, 0xbfb8aa3b, v16
	v_exp_f32_e32 v16, v16
	s_nop 0
	v_add_f32_e32 v16, 1.0, v16
	v_rcp_f32_e32 v16, v16
	s_nop 0
	v_mul_f32_e32 v11, v16, v11
	v_add_f32_e32 v16, v81, v14
	v_mul_f32_e32 v11, v16, v11
	v_bfe_u32 v16, v10, 16, 1
	v_add3_u32 v10, v10, v16, s8
	v_bfe_u32 v16, v11, 16, 1
	v_lshrrev_b32_e32 v10, 16, v10
	v_add3_u32 v11, v11, v16, s8
	v_and_or_b32 v16, v11, s58, v10
	v_add_co_u32_e32 v10, vcc, s25, v12
	s_nop 1
	v_addc_co_u32_e32 v11, vcc, 0, v13, vcc
	global_store_dword v[10:11], v16, off offset:2048
	v_lshlrev_b32_e32 v10, 16, v8
	v_exp_f32_e32 v10, v10
	v_and_b32_e32 v8, 0xffff0000, v8
	v_fma_f32 v11, -v10, v10, 1.0
	v_max_f32_e32 v11, 0, v11
	v_sqrt_f32_e32 v11, v11
	s_nop 0
	v_mul_f32_e32 v11, v11, v8
	v_lshlrev_b32_e32 v8, 16, v9
	v_exp_f32_e32 v8, v8
	v_fmac_f32_e32 v11, v10, v15
	v_and_b32_e32 v9, 0xffff0000, v9
	v_fma_f32 v10, -v8, v8, 1.0
	v_max_f32_e32 v10, 0, v10
	v_sqrt_f32_e32 v10, v10
	s_nop 0
	v_mul_f32_e32 v10, v10, v9
	v_fmac_f32_e32 v10, v8, v14
	v_lshlrev_b32_e32 v8, 16, v101
	v_mul_f32_e32 v14, 0x3d372713, v8
	v_mul_f32_e32 v14, v14, v8
	v_fma_f32 v14, v14, v8, v8
	v_mul_f32_e32 v14, 0x3fcc422a, v14
	v_mul_f32_e32 v14, 0xbfb8aa3b, v14
	v_exp_f32_e32 v14, v14
	v_and_b32_e32 v9, 0xffff0000, v101
	v_add_f32_e32 v14, 1.0, v14
	v_rcp_f32_e32 v14, v14
	s_nop 0
	v_mul_f32_e32 v8, v14, v8
	v_add_f32_e32 v14, v80, v11
	v_mul_f32_e32 v8, v14, v8
	v_mul_f32_e32 v14, 0x3d372713, v9
	v_mul_f32_e32 v14, v14, v9
	v_fma_f32 v14, v14, v9, v9
	v_mul_f32_e32 v14, 0x3fcc422a, v14
	v_mul_f32_e32 v14, 0xbfb8aa3b, v14
	v_exp_f32_e32 v14, v14
	s_nop 0
	v_add_f32_e32 v14, 1.0, v14
	v_rcp_f32_e32 v14, v14
	s_nop 0
	v_mul_f32_e32 v9, v14, v9
	v_add_f32_e32 v14, v79, v10
	v_mul_f32_e32 v9, v14, v9
	v_bfe_u32 v14, v8, 16, 1
	v_add3_u32 v8, v8, v14, s8
	v_bfe_u32 v14, v9, 16, 1
	v_lshrrev_b32_e32 v8, 16, v8
	v_add3_u32 v9, v9, v14, s8
	v_and_or_b32 v14, v9, s58, v8
	v_add_co_u32_e32 v8, vcc, s3, v12
	s_movk_i32 s3, 0x1000
	s_nop 0
	v_addc_co_u32_e32 v9, vcc, 0, v13, vcc
	global_store_dword v[8:9], v14, off offset:512
	v_lshlrev_b32_e32 v8, 16, v6
	v_exp_f32_e32 v8, v8
	v_and_b32_e32 v6, 0xffff0000, v6
	v_fma_f32 v9, -v8, v8, 1.0
	v_max_f32_e32 v9, 0, v9
	v_sqrt_f32_e32 v9, v9
	s_nop 0
	v_mul_f32_e32 v9, v9, v6
	v_lshlrev_b32_e32 v6, 16, v7
	v_exp_f32_e32 v6, v6
	v_fmac_f32_e32 v9, v8, v11
	v_and_b32_e32 v7, 0xffff0000, v7
	v_fma_f32 v8, -v6, v6, 1.0
	v_max_f32_e32 v8, 0, v8
	v_sqrt_f32_e32 v8, v8
	s_nop 0
	v_mul_f32_e32 v8, v8, v7
	v_fmac_f32_e32 v8, v6, v10
	v_lshlrev_b32_e32 v6, 16, v99
	v_mul_f32_e32 v10, 0x3d372713, v6
	v_mul_f32_e32 v10, v10, v6
	v_fma_f32 v10, v10, v6, v6
	v_mul_f32_e32 v10, 0x3fcc422a, v10
	v_mul_f32_e32 v10, 0xbfb8aa3b, v10
	v_exp_f32_e32 v10, v10
	v_and_b32_e32 v7, 0xffff0000, v99
	v_add_f32_e32 v10, 1.0, v10
; __device__ __forceinline__ unsigned pk2(float lo, float hi) { return f2bf(lo) | (f2bf(hi) << 16); }
; __device__ __forceinline__ float fast_sigmoid(float x) { return fast_rcp(1.f + fast_exp2(-1.4426950408889634f * x)); }
; #define LRU_STEP(h, l, x) do { const float a_ = fast_exp2(l); h = fmaf(a_, h, __builtin_amdgcn_sqrtf(fmaxf(fmaf(-a_, a_, 1.f), 0.f)) * (x)); } while (0)
; __global__ void __launch_bounds__(NTHREADS, 2) mega(Args args) {
;     ...
;                 for (int it = gw; it < BATCH * 72 * 22; it += NGW) {
;                     const int cg = it % 22, r1 = it / 22, q = r1 % 72, b = r1 / 72;
;                     const int ch = cg * 128 + 2 * lane;
;                     const int rbase = q < 8 ? ML + b * CTX + 32 * q : b * SEQ + 32 * (q - 8);
;                     const size_t ro = (size_t)rbase * LW + ch;
;     ...
; #pragma unroll
;                       for (int t = 31; t >= 0; --t) { LRU_STEP(h0, bf_lo(lb[t].x), bf_hi(lb[t].x)); LRU_STEP(h1, bf_lo(lb[t].y), bf_hi(lb[t].y));
;                           const float g0 = bf_lo(gwv[t]), g1 = bf_hi(gwv[t]);
;                           const float z0 = g0 * fast_sigmoid(1.5957691216057308f * (g0 + 0.044715f * g0 * g0 * g0)) * (hf0[t] + h0);
;                           const float z1 = g1 * fast_sigmoid(1.5957691216057308f * (g1 + 0.044715f * g1 * g1 * g1)) * (hf1[t] + h1);
;                           *(unsigned*)(Zb + ro + (size_t)t * LW) = pk2(z0, z1); } }
	v_rcp_f32_e32 v10, v10
	s_nop 0
	v_mul_f32_e32 v6, v10, v6
	v_add_f32_e32 v10, v78, v9
	v_mul_f32_e32 v6, v10, v6
	v_mul_f32_e32 v10, 0x3d372713, v7
	v_mul_f32_e32 v10, v10, v7
	v_fma_f32 v10, v10, v7, v7
	v_mul_f32_e32 v10, 0x3fcc422a, v10
	v_mul_f32_e32 v10, 0xbfb8aa3b, v10
	v_exp_f32_e32 v10, v10
	s_nop 0
	v_add_f32_e32 v10, 1.0, v10
	v_rcp_f32_e32 v10, v10
	s_nop 0
	v_mul_f32_e32 v7, v10, v7
	v_add_f32_e32 v10, v77, v8
	v_mul_f32_e32 v7, v10, v7
	v_bfe_u32 v10, v6, 16, 1
	v_add3_u32 v6, v6, v10, s8
	v_bfe_u32 v10, v7, 16, 1
	v_lshrrev_b32_e32 v6, 16, v6
	v_add3_u32 v7, v7, v10, s8
	v_and_or_b32 v10, v7, s58, v6
	v_add_co_u32_e32 v6, vcc, s9, v12
	s_nop 1
	v_addc_co_u32_e32 v7, vcc, 0, v13, vcc
	global_store_dword v[6:7], v10, off offset:3072
	v_lshlrev_b32_e32 v6, 16, v4
	v_exp_f32_e32 v6, v6
	v_and_b32_e32 v4, 0xffff0000, v4
	v_fma_f32 v7, -v6, v6, 1.0
	v_max_f32_e32 v7, 0, v7
	v_sqrt_f32_e32 v7, v7
	s_nop 0
	v_mul_f32_e32 v7, v7, v4
	v_lshlrev_b32_e32 v4, 16, v5
	v_exp_f32_e32 v4, v4
	v_fmac_f32_e32 v7, v6, v9
	v_and_b32_e32 v5, 0xffff0000, v5
	v_fma_f32 v6, -v4, v4, 1.0
	v_max_f32_e32 v6, 0, v6
	v_sqrt_f32_e32 v6, v6
	s_nop 0
	v_mul_f32_e32 v6, v6, v5
	v_fmac_f32_e32 v6, v4, v8
	v_lshlrev_b32_e32 v4, 16, v96
	v_mul_f32_e32 v8, 0x3d372713, v4
	v_mul_f32_e32 v8, v8, v4
	v_fma_f32 v8, v8, v4, v4
	v_mul_f32_e32 v8, 0x3fcc422a, v8
	v_mul_f32_e32 v8, 0xbfb8aa3b, v8
	v_exp_f32_e32 v8, v8
	v_and_b32_e32 v5, 0xffff0000, v96
	v_add_f32_e32 v8, 1.0, v8
	v_rcp_f32_e32 v8, v8
	s_nop 0
	v_mul_f32_e32 v4, v8, v4
	v_add_f32_e32 v8, v76, v7
	v_mul_f32_e32 v4, v8, v4
	v_mul_f32_e32 v8, 0x3d372713, v5
	v_mul_f32_e32 v8, v8, v5
	v_fma_f32 v8, v8, v5, v5
	v_mul_f32_e32 v8, 0x3fcc422a, v8
	v_mul_f32_e32 v8, 0xbfb8aa3b, v8
	v_exp_f32_e32 v8, v8
	s_nop 0
	v_add_f32_e32 v8, 1.0, v8
	v_rcp_f32_e32 v8, v8
	s_nop 0
	v_mul_f32_e32 v5, v8, v5
	v_add_f32_e32 v8, v75, v6
	v_mul_f32_e32 v5, v8, v5
	v_bfe_u32 v8, v4, 16, 1
	v_add3_u32 v4, v4, v8, s8
	v_bfe_u32 v8, v5, 16, 1
	v_lshrrev_b32_e32 v4, 16, v4
	v_add3_u32 v5, v5, v8, s8
	v_and_or_b32 v8, v5, s58, v4
	v_add_co_u32_e32 v4, vcc, s3, v12
	s_nop 1
	v_addc_co_u32_e32 v5, vcc, 0, v13, vcc
	global_store_dword v[4:5], v8, off offset:1536
	v_lshlrev_b32_e32 v4, 16, v2
	v_exp_f32_e32 v4, v4
	v_and_b32_e32 v2, 0xffff0000, v2
	v_fma_f32 v5, -v4, v4, 1.0
	v_max_f32_e32 v5, 0, v5
	v_sqrt_f32_e32 v5, v5
	s_nop 0
	v_mul_f32_e32 v2, v5, v2
	v_fmac_f32_e32 v2, v4, v7
	v_lshlrev_b32_e32 v4, 16, v3
	v_exp_f32_e32 v4, v4
	v_and_b32_e32 v3, 0xffff0000, v3
	v_add_f32_e32 v2, v74, v2
	v_fma_f32 v5, -v4, v4, 1.0
	v_max_f32_e32 v5, 0, v5
	v_sqrt_f32_e32 v5, v5
	s_nop 0
	v_mul_f32_e32 v3, v5, v3
	v_fmac_f32_e32 v3, v4, v6
	v_lshlrev_b32_e32 v4, 16, v93
	v_mul_f32_e32 v6, 0x3d372713, v4
	v_mul_f32_e32 v6, v6, v4
	v_fma_f32 v6, v6, v4, v4
	v_mul_f32_e32 v6, 0x3fcc422a, v6
	v_mul_f32_e32 v6, 0xbfb8aa3b, v6
	v_exp_f32_e32 v6, v6
	v_and_b32_e32 v5, 0xffff0000, v93
	v_add_f32_e32 v3, v73, v3
	v_add_f32_e32 v6, 1.0, v6
	v_rcp_f32_e32 v6, v6
	s_nop 0
	v_mul_f32_e32 v4, v6, v4
	v_mul_f32_e32 v2, v2, v4
	v_mul_f32_e32 v4, 0x3d372713, v5
	v_mul_f32_e32 v4, v4, v5
	v_fma_f32 v4, v4, v5, v5
	v_mul_f32_e32 v4, 0x3fcc422a, v4
	v_mul_f32_e32 v4, 0xbfb8aa3b, v4
	v_exp_f32_e32 v4, v4
	s_nop 0
	v_add_f32_e32 v4, 1.0, v4
	v_rcp_f32_e32 v4, v4
	s_nop 0
	v_mul_f32_e32 v4, v4, v5
	v_mul_f32_e32 v3, v3, v4
	v_bfe_u32 v4, v2, 16, 1
	v_add3_u32 v2, v2, v4, s8
	v_bfe_u32 v4, v3, 16, 1
	v_lshrrev_b32_e32 v2, 16, v2
	v_add3_u32 v3, v3, v4, s8
	v_and_or_b32 v2, v3, s58, v2
	global_store_dword v[12:13], v2, off
	s_cbranch_scc0 .LBB9_1050
.LBB9_1046:
	s_sub_i32 s80, 0x18bf, s14
	s_mul_hi_i32 s3, s80, 0x2e8ba2e9
	s_lshr_b32 s4, s3, 31
	s_ashr_i32 s5, s3, 2
	s_add_i32 s5, s5, s4
	s_mul_hi_i32 s3, s5, 0x38e38e39
	s_lshr_b32 s4, s3, 31
	s_ashr_i32 s3, s3, 4
	s_add_i32 s3, s3, s4
	s_mulk_i32 s3, 0x48
	s_sub_i32 s4, s5, s3
	s_mul_hi_i32 s3, s80, 0xa57eb503
	s_add_i32 s3, s3, s80
	s_lshr_b32 s9, s3, 31
	s_ashr_i32 s21, s3, 10
	s_add_i32 s21, s21, s9
	s_cmp_gt_i32 s4, 7
	s_mov_b64 s[10:11], -1
	s_cbranch_scc0 .LBB9_1048
	s_lshl_b32 s3, s21, 11
	s_lshl_b32 s9, s4, 5
	s_add_i32 s3, s3, s9
	s_add_i32 s20, s3, 0xffffff00
	s_mov_b64 s[10:11], 0
